# prep_dn_chunk fused into DeltaNet D1: k/v/q tiles computed from proj rows in registers (only q kept in dq for fragment loads), dk/dv round trip removed
# baseline (speedup 1.0000x reference)
;     template <class Tp> __device__ __forceinline__ Tp* W(size_t off) const { return (Tp*)(ws + off); }
; __device__ __forceinline__ void prep_dn_load(const bf16_t* proj, const float* cw, int idx, u32x4 (&raw)[4], int& t, int& ch) {
;     if (idx >= 0) { t = idx / 384; const int j = idx - t * 384; ch = j * 8; }
; #pragma unroll
;     for (int k = 0; k < 4; ++k) { const int tt = t - 3 + k; raw[k] = (u32x4){0u, 0u, 0u, 0u};
;         if (tt >= 0) raw[k] = *(const u32x4*)(proj + (size_t)tt * NP + C_DNQ + ch); }
; }
; __device__ __forceinline__ void prep_dn_finish(const float* cw, bf16_t* dq, bf16_t* dk, bf16_t* dv, const u32x4 (&raw)[4], int t, int ch) {
;     float a[8];
; #pragma unroll
;     for (int e = 0; e < 8; ++e) a[e] = 0.f;
; #pragma unroll
;     for (int k = 0; k < 4; ++k) {
;         const f32x4 w0 = *(const f32x4*)(cw + k * 3072 + ch), w1 = *(const f32x4*)(cw + k * 3072 + ch + 4);
; __device__ void dn_d1(const Ctx& c, int ip) {
;     const bf16_t* proj = c.W<bf16_t>(WS_PROJ);
;     const bf16_t* dq = c.W<bf16_t>(WS_DQ); const bf16_t* dk = c.W<bf16_t>(WS_DK); const bf16_t* dv = c.W<bf16_t>(WS_DV);
;     const int tid = c.tid, half = tid >> 8, lt = tid & 255, lw = c.wave & 3, r = c.r, q = c.q;
;     const int item = ip * 2 + half, ck = item >> 3, h = item & 7, t0 = ck * 64;
;     float* Ms = c.ldsf + half * (64 * 68 + 128); float* beta_s = Ms + 64 * 68; float* gc_s = beta_s + 64;
;     const size_t ch = (size_t)(ck * 8 + h);
.Ldnd_entry:
	s_mov_b64 exec, -1
	v_readlane_b32 s0, v247, 1
	v_readlane_b32 s1, v247, 2
	v_readlane_b32 s6, v247, 0
	v_readlane_b32 s16, v248, 25
	v_readfirstlane_b32 s9, v234
	s_load_dwordx2 s[4:5], s[0:1], 0xe8
	s_load_dwordx4 s[32:35], s[0:1], 0x28
	s_lshr_b32 s16, s16, 3
	s_lshr_b32 s9, s9, 6
	s_lshr_b32 s7, s6, 1
	s_and_b32 s8, s6, 1
	s_and_b32 s10, s9, 3
	s_lshr_b32 s11, s9, 2
	s_lshl_b32 s15, s7, 6
	s_mul_i32 s24, s11, 0xd000
	v_and_b32_e32 v0, 0xff, v234
	v_and_b32_e32 v3, 63, v234
	v_and_b32_e32 v1, 15, v234
	v_bfe_u32 v2, v234, 4, 2
	s_load_dwordx2 s[40:41], s[0:1], 0x20
	s_mul_i32 s22, s16, 0xc000
	s_mov_b32 s36, 0xbfb8aa3b
	s_mov_b32 s37, 0xbfb8aa3b
	s_mov_b32 s38, 1.0
	s_mov_b32 s39, 1.0
	s_waitcnt lgkmcnt(0)
	s_add_u32 s40, s40, s22
	s_addc_u32 s41, s41, 0
	s_mov_b32 s12, 0
	s_waitcnt lgkmcnt(0)
.Ldnd_call:
	s_lshl_b32 s13, s8, 2
	s_lshl_b32 s22, s12, 1
	s_add_u32 s13, s13, s22
	s_add_u32 s13, s13, s11
	s_lshl_b32 s14, s7, 3
	s_add_u32 s14, s14, s13
	v_lshrrev_b32_e32 v12, 4, v0
	v_and_b32_e32 v13, 15, v0
	s_lshl_b32 s22, s15, 11
	s_lshl_b32 s23, s13, 8
	s_add_u32 s22, s22, s23
	v_lshlrev_b32_e32 v5, 11, v12
	v_lshl_add_u32 v5, v13, 4, v5
	v_add_u32_e32 v5, s22, v5
	v_mul_u32_u24_e32 v6, 272, v12
	v_lshl_add_u32 v6, v13, 4, v6
	v_add_u32_e32 v6, s24, v6
	s_lshl_b32 s22, s14, 14
	v_lshl_add_u32 v7, v0, 4, s22
	v_lshl_add_u32 v8, v12, 2, s24
	s_waitcnt vmcnt(0) lgkmcnt(0)
	s_barrier
	v_lshrrev_b32_e32 v12, 4, v0
	v_add_u32_e32 v14, s15, v12
	s_mov_b32 s25, 0x7e00
	v_mul_lo_u32 v14, v14, s25
	v_and_b32_e32 v13, 15, v0
	s_lshl_b32 s22, s13, 7
	v_lshl_add_u32 v13, v13, 3, s22
	v_lshl_add_u32 v14, v13, 1, v14
	v_lshlrev_b32_e32 v15, 2, v13
	s_add_u32 vcc_lo, s40, 0x1000
	s_addc_u32 vcc_hi, s41, 0
	global_load_dwordx4 v[128:131], v15, vcc
	global_load_dwordx4 v[132:135], v15, vcc offset:16
	s_add_u32 vcc_lo, s40, 0x4000
	s_addc_u32 vcc_hi, s41, 0
	global_load_dwordx4 v[136:139], v15, vcc
	global_load_dwordx4 v[140:143], v15, vcc offset:16
	s_add_u32 vcc_lo, s40, 0x7000
	s_addc_u32 vcc_hi, s41, 0
	global_load_dwordx4 v[144:147], v15, vcc
	global_load_dwordx4 v[148:151], v15, vcc offset:16
	s_add_u32 vcc_lo, s40, 0xa000
	s_addc_u32 vcc_hi, s41, 0
	global_load_dwordx4 v[152:155], v15, vcc
	global_load_dwordx4 v[156:159], v15, vcc offset:16
	s_add_u32 s22, s4, 0x9be8e00
	s_addc_u32 s23, s5, 0
	global_load_dwordx4 v[64:67], v14, s[22:23]
	s_add_u32 s22, s4, 0x9bf0c00
	s_addc_u32 s23, s5, 0
	global_load_dwordx4 v[68:71], v14, s[22:23]
	s_add_u32 s22, s4, 0x9bf8a00
	s_addc_u32 s23, s5, 0
	global_load_dwordx4 v[72:75], v14, s[22:23]
	s_add_u32 s22, s4, 0x9c00800
	s_addc_u32 s23, s5, 0
	global_load_dwordx4 v[76:79], v14, s[22:23]
	s_add_u32 s22, s4, 0x9c66e00
	s_addc_u32 s23, s5, 0
	global_load_dwordx4 v[80:83], v14, s[22:23]
	s_add_u32 s22, s4, 0x9c6ec00
	s_addc_u32 s23, s5, 0
	global_load_dwordx4 v[84:87], v14, s[22:23]
	s_add_u32 s22, s4, 0x9c76a00
	s_addc_u32 s23, s5, 0
	global_load_dwordx4 v[88:91], v14, s[22:23]
	s_add_u32 s22, s4, 0x9c7e800
	s_addc_u32 s23, s5, 0
	global_load_dwordx4 v[92:95], v14, s[22:23]
	s_add_u32 s22, s4, 0x9ce4e00
	s_addc_u32 s23, s5, 0
	global_load_dwordx4 v[96:99], v14, s[22:23]
	s_add_u32 s22, s4, 0x9cecc00
	s_addc_u32 s23, s5, 0
	global_load_dwordx4 v[100:103], v14, s[22:23]
	s_add_u32 s22, s4, 0x9cf4a00
	s_addc_u32 s23, s5, 0
	global_load_dwordx4 v[104:107], v14, s[22:23]
	s_add_u32 s22, s4, 0x9cfc800
	s_addc_u32 s23, s5, 0
	global_load_dwordx4 v[108:111], v14, s[22:23]
	s_add_u32 s22, s4, 0x9d62e00
	s_addc_u32 s23, s5, 0
	global_load_dwordx4 v[112:115], v14, s[22:23]
	s_add_u32 s22, s4, 0x9d6ac00
	s_addc_u32 s23, s5, 0
	global_load_dwordx4 v[116:119], v14, s[22:23]
	s_add_u32 s22, s4, 0x9d72a00
	s_addc_u32 s23, s5, 0
	global_load_dwordx4 v[120:123], v14, s[22:23]
	s_add_u32 s22, s4, 0x9d7a800
	s_addc_u32 s23, s5, 0
	global_load_dwordx4 v[124:127], v14, s[22:23]
	s_waitcnt vmcnt(0)
	s_cmp_lg_u32 s7, 0
	s_cbranch_scc1 .Ldnd_nz0
	v_mov_b32_e32 v13, 0
	v_cmp_gt_u32_e32 vcc, 3, v12
	v_cndmask_b32_e32 v64, v64, v13, vcc
	v_cndmask_b32_e32 v65, v65, v13, vcc
	v_cndmask_b32_e32 v66, v66, v13, vcc
	v_cndmask_b32_e32 v67, v67, v13, vcc
	v_cmp_gt_u32_e32 vcc, 2, v12
	v_cndmask_b32_e32 v68, v68, v13, vcc
	v_cndmask_b32_e32 v69, v69, v13, vcc
	v_cndmask_b32_e32 v70, v70, v13, vcc
	v_cndmask_b32_e32 v71, v71, v13, vcc
	v_cmp_gt_u32_e32 vcc, 1, v12
	v_cndmask_b32_e32 v72, v72, v13, vcc
	v_cndmask_b32_e32 v73, v73, v13, vcc
	v_cndmask_b32_e32 v74, v74, v13, vcc
	v_cndmask_b32_e32 v75, v75, v13, vcc
; __device__ __forceinline__ unsigned pk2(float lo, float hi) { const f32v2_t v = {lo, hi}; const bf16v2_t b = __builtin_convertvector(v, bf16v2_t); return __builtin_bit_cast(unsigned, b); }
; __device__ __forceinline__ float lo16(unsigned u) { return __uint_as_float(u << 16); }
; __device__ __forceinline__ float hi16(unsigned u) { return __uint_as_float(u & 0xffff0000u); }
; __device__ __forceinline__ float siluf_(float x) { return x * __builtin_amdgcn_rcpf(1.0f + __expf(-x)); }
; __device__ __forceinline__ void prep_dn_finish(const float* cw, bf16_t* dq, bf16_t* dk, bf16_t* dv, const u32x4 (&raw)[4], int t, int ch) {
;     float a[8];
; #pragma unroll
;     for (int e = 0; e < 8; ++e) a[e] = 0.f;
; #pragma unroll
;     for (int k = 0; k < 4; ++k) {
;         const f32x4 w0 = *(const f32x4*)(cw + k * 3072 + ch), w1 = *(const f32x4*)(cw + k * 3072 + ch + 4);
;         a[0] += w0[0] * lo16(raw[k].x); a[1] += w0[1] * hi16(raw[k].x); a[2] += w0[2] * lo16(raw[k].y); a[3] += w0[3] * hi16(raw[k].y);
;         a[4] += w1[0] * lo16(raw[k].z); a[5] += w1[1] * hi16(raw[k].z); a[6] += w1[2] * lo16(raw[k].w); a[7] += w1[3] * hi16(raw[k].w); }
;     float ss = 0.f;
; #pragma unroll
;     for (int e = 0; e < 8; ++e) { a[e] = siluf_(a[e]); ss += a[e] * a[e]; }
;     ss += __shfl_xor(ss, 1); ss += __shfl_xor(ss, 2); ss += __shfl_xor(ss, 4); ss += __shfl_xor(ss, 8);
;     float sc = 1.0f;
;     if (ch < 2048) { sc = rsqrtf(ss + EPS); if (ch < 1024) sc *= 0.08838834764831845f; }
;     u32x4 w; w.x = pk2(a[0] * sc, a[1] * sc); w.y = pk2(a[2] * sc, a[3] * sc); w.z = pk2(a[4] * sc, a[5] * sc); w.w = pk2(a[6] * sc, a[7] * sc);
;     bf16_t* dst = (ch < 1024) ? dq : (ch < 2048 ? dk : dv);
;     *(u32x4*)(dst + (size_t)t * 1024 + (ch & 1023)) = w;
.Ldnd_nz0:
	v_lshlrev_b32_e32 v160, 16, v64
	v_and_b32_e32 v161, 0xffff0000, v64
	v_lshlrev_b32_e32 v162, 16, v65
	v_and_b32_e32 v163, 0xffff0000, v65
	v_lshlrev_b32_e32 v164, 16, v66
	v_and_b32_e32 v165, 0xffff0000, v66
	v_lshlrev_b32_e32 v166, 16, v67
	v_and_b32_e32 v167, 0xffff0000, v67
	v_pk_mul_f32 v[168:169], v[128:129], v[160:161]
	v_pk_mul_f32 v[170:171], v[130:131], v[162:163]
	v_pk_mul_f32 v[172:173], v[132:133], v[164:165]
	v_pk_mul_f32 v[174:175], v[134:135], v[166:167]
	v_lshlrev_b32_e32 v160, 16, v68
	v_and_b32_e32 v161, 0xffff0000, v68
	v_lshlrev_b32_e32 v162, 16, v69
	v_and_b32_e32 v163, 0xffff0000, v69
	v_lshlrev_b32_e32 v164, 16, v70
	v_and_b32_e32 v165, 0xffff0000, v70
	v_lshlrev_b32_e32 v166, 16, v71
	v_and_b32_e32 v167, 0xffff0000, v71
	v_pk_fma_f32 v[168:169], v[136:137], v[160:161], v[168:169]
	v_pk_fma_f32 v[170:171], v[138:139], v[162:163], v[170:171]
	v_pk_fma_f32 v[172:173], v[140:141], v[164:165], v[172:173]
	v_pk_fma_f32 v[174:175], v[142:143], v[166:167], v[174:175]
	v_lshlrev_b32_e32 v160, 16, v72
	v_and_b32_e32 v161, 0xffff0000, v72
	v_lshlrev_b32_e32 v162, 16, v73
	v_and_b32_e32 v163, 0xffff0000, v73
	v_lshlrev_b32_e32 v164, 16, v74
	v_and_b32_e32 v165, 0xffff0000, v74
	v_lshlrev_b32_e32 v166, 16, v75
	v_and_b32_e32 v167, 0xffff0000, v75
	v_pk_fma_f32 v[168:169], v[144:145], v[160:161], v[168:169]
	v_pk_fma_f32 v[170:171], v[146:147], v[162:163], v[170:171]
	v_pk_fma_f32 v[172:173], v[148:149], v[164:165], v[172:173]
	v_pk_fma_f32 v[174:175], v[150:151], v[166:167], v[174:175]
	v_lshlrev_b32_e32 v160, 16, v76
	v_and_b32_e32 v161, 0xffff0000, v76
	v_lshlrev_b32_e32 v162, 16, v77
	v_and_b32_e32 v163, 0xffff0000, v77
	v_lshlrev_b32_e32 v164, 16, v78
	v_and_b32_e32 v165, 0xffff0000, v78
	v_lshlrev_b32_e32 v166, 16, v79
	v_and_b32_e32 v167, 0xffff0000, v79
	v_pk_fma_f32 v[168:169], v[152:153], v[160:161], v[168:169]
	v_pk_fma_f32 v[170:171], v[154:155], v[162:163], v[170:171]
	v_pk_fma_f32 v[172:173], v[156:157], v[164:165], v[172:173]
	v_pk_fma_f32 v[174:175], v[158:159], v[166:167], v[174:175]
	v_pk_mul_f32 v[160:161], v[168:169], s[36:37]
	v_pk_mul_f32 v[162:163], v[170:171], s[36:37]
	v_pk_mul_f32 v[164:165], v[172:173], s[36:37]
	v_pk_mul_f32 v[166:167], v[174:175], s[36:37]
	v_exp_f32_e32 v160, v160
	v_exp_f32_e32 v161, v161
	v_exp_f32_e32 v162, v162
	v_exp_f32_e32 v163, v163
	v_exp_f32_e32 v164, v164
	v_exp_f32_e32 v165, v165
	v_exp_f32_e32 v166, v166
	v_exp_f32_e32 v167, v167
	v_pk_add_f32 v[160:161], v[160:161], s[38:39]
	v_pk_add_f32 v[162:163], v[162:163], s[38:39]
	v_pk_add_f32 v[164:165], v[164:165], s[38:39]
	v_pk_add_f32 v[166:167], v[166:167], s[38:39]
	v_rcp_f32_e32 v160, v160
	v_rcp_f32_e32 v161, v161
	v_rcp_f32_e32 v162, v162
	v_rcp_f32_e32 v163, v163
	v_rcp_f32_e32 v164, v164
	v_rcp_f32_e32 v165, v165
	v_rcp_f32_e32 v166, v166
	v_rcp_f32_e32 v167, v167
	v_pk_mul_f32 v[168:169], v[168:169], v[160:161]
	v_pk_mul_f32 v[170:171], v[170:171], v[162:163]
	v_pk_mul_f32 v[172:173], v[172:173], v[164:165]
	v_pk_mul_f32 v[174:175], v[174:175], v[166:167]
	v_pk_mul_f32 v[160:161], v[168:169], v[168:169]
	v_pk_fma_f32 v[160:161], v[170:171], v[170:171], v[160:161]
	v_pk_fma_f32 v[160:161], v[172:173], v[172:173], v[160:161]
	v_pk_fma_f32 v[160:161], v[174:175], v[174:175], v[160:161]
	s_nop 0
	v_add_f32_e32 v162, v160, v161
	s_nop 1
	v_add_f32_dpp v162, v162, v162 quad_perm:[1,0,3,2] row_mask:0xf bank_mask:0xf
	s_nop 1
	v_add_f32_dpp v162, v162, v162 quad_perm:[2,3,0,1] row_mask:0xf bank_mask:0xf
	s_nop 1
	v_add_f32_dpp v162, v162, v162 row_half_mirror row_mask:0xf bank_mask:0xf
	s_nop 1
	v_add_f32_dpp v162, v162, v162 row_mirror row_mask:0xf bank_mask:0xf
	v_add_f32_e32 v162, 0x358637bd, v162
	v_rsq_f32_e32 v162, v162
	s_nop 0
	v_pk_mul_f32 v[168:169], v[168:169], v[162:163] op_sel_hi:[1,0]
	v_pk_mul_f32 v[170:171], v[170:171], v[162:163] op_sel_hi:[1,0]
	v_pk_mul_f32 v[172:173], v[172:173], v[162:163] op_sel_hi:[1,0]
	v_pk_mul_f32 v[174:175], v[174:175], v[162:163] op_sel_hi:[1,0]
	v_cvt_pk_bf16_f32 v16, v168, v169
	v_cvt_pk_bf16_f32 v17, v170, v171
	v_cvt_pk_bf16_f32 v18, v172, v173
	v_cvt_pk_bf16_f32 v19, v174, v175
	v_lshlrev_b32_e32 v160, 16, v80
	v_and_b32_e32 v161, 0xffff0000, v80
	v_lshlrev_b32_e32 v162, 16, v81
	v_and_b32_e32 v163, 0xffff0000, v81
	v_lshlrev_b32_e32 v164, 16, v82
	v_and_b32_e32 v165, 0xffff0000, v82
	v_lshlrev_b32_e32 v166, 16, v83
	v_and_b32_e32 v167, 0xffff0000, v83
	v_pk_mul_f32 v[168:169], v[128:129], v[160:161]
	v_pk_mul_f32 v[170:171], v[130:131], v[162:163]
	v_pk_mul_f32 v[172:173], v[132:133], v[164:165]
	v_pk_mul_f32 v[174:175], v[134:135], v[166:167]
	v_lshlrev_b32_e32 v160, 16, v84
	v_and_b32_e32 v161, 0xffff0000, v84
	v_lshlrev_b32_e32 v162, 16, v85
	v_and_b32_e32 v163, 0xffff0000, v85
	v_lshlrev_b32_e32 v164, 16, v86
	v_and_b32_e32 v165, 0xffff0000, v86
	v_lshlrev_b32_e32 v166, 16, v87
	v_and_b32_e32 v167, 0xffff0000, v87
	v_pk_fma_f32 v[168:169], v[136:137], v[160:161], v[168:169]
	v_pk_fma_f32 v[170:171], v[138:139], v[162:163], v[170:171]
	v_pk_fma_f32 v[172:173], v[140:141], v[164:165], v[172:173]
	v_pk_fma_f32 v[174:175], v[142:143], v[166:167], v[174:175]
	v_lshlrev_b32_e32 v160, 16, v88
	v_and_b32_e32 v161, 0xffff0000, v88
	v_lshlrev_b32_e32 v162, 16, v89
	v_and_b32_e32 v163, 0xffff0000, v89
	v_lshlrev_b32_e32 v164, 16, v90
	v_and_b32_e32 v165, 0xffff0000, v90
	v_lshlrev_b32_e32 v166, 16, v91
	v_and_b32_e32 v167, 0xffff0000, v91
	v_pk_fma_f32 v[168:169], v[144:145], v[160:161], v[168:169]
	v_pk_fma_f32 v[170:171], v[146:147], v[162:163], v[170:171]
	v_pk_fma_f32 v[172:173], v[148:149], v[164:165], v[172:173]
	v_pk_fma_f32 v[174:175], v[150:151], v[166:167], v[174:175]
; __device__ __forceinline__ unsigned pk2(float lo, float hi) { const f32v2_t v = {lo, hi}; const bf16v2_t b = __builtin_convertvector(v, bf16v2_t); return __builtin_bit_cast(unsigned, b); }
; __device__ __forceinline__ float lo16(unsigned u) { return __uint_as_float(u << 16); }
; __device__ __forceinline__ float hi16(unsigned u) { return __uint_as_float(u & 0xffff0000u); }
; __device__ __forceinline__ float siluf_(float x) { return x * __builtin_amdgcn_rcpf(1.0f + __expf(-x)); }
; __device__ __forceinline__ void prep_dn_finish(const float* cw, bf16_t* dq, bf16_t* dk, bf16_t* dv, const u32x4 (&raw)[4], int t, int ch) {
;     float a[8];
; #pragma unroll
;     for (int e = 0; e < 8; ++e) a[e] = 0.f;
; #pragma unroll
;     for (int k = 0; k < 4; ++k) {
;         const f32x4 w0 = *(const f32x4*)(cw + k * 3072 + ch), w1 = *(const f32x4*)(cw + k * 3072 + ch + 4);
;         a[0] += w0[0] * lo16(raw[k].x); a[1] += w0[1] * hi16(raw[k].x); a[2] += w0[2] * lo16(raw[k].y); a[3] += w0[3] * hi16(raw[k].y);
;         a[4] += w1[0] * lo16(raw[k].z); a[5] += w1[1] * hi16(raw[k].z); a[6] += w1[2] * lo16(raw[k].w); a[7] += w1[3] * hi16(raw[k].w); }
;     float ss = 0.f;
; #pragma unroll
;     for (int e = 0; e < 8; ++e) { a[e] = siluf_(a[e]); ss += a[e] * a[e]; }
;     ss += __shfl_xor(ss, 1); ss += __shfl_xor(ss, 2); ss += __shfl_xor(ss, 4); ss += __shfl_xor(ss, 8);
;     float sc = 1.0f;
;     if (ch < 2048) { sc = rsqrtf(ss + EPS); if (ch < 1024) sc *= 0.08838834764831845f; }
;     u32x4 w; w.x = pk2(a[0] * sc, a[1] * sc); w.y = pk2(a[2] * sc, a[3] * sc); w.z = pk2(a[4] * sc, a[5] * sc); w.w = pk2(a[6] * sc, a[7] * sc);
	v_lshlrev_b32_e32 v160, 16, v92
	v_and_b32_e32 v161, 0xffff0000, v92
	v_lshlrev_b32_e32 v162, 16, v93
	v_and_b32_e32 v163, 0xffff0000, v93
	v_lshlrev_b32_e32 v164, 16, v94
	v_and_b32_e32 v165, 0xffff0000, v94
	v_lshlrev_b32_e32 v166, 16, v95
	v_and_b32_e32 v167, 0xffff0000, v95
	v_pk_fma_f32 v[168:169], v[152:153], v[160:161], v[168:169]
	v_pk_fma_f32 v[170:171], v[154:155], v[162:163], v[170:171]
	v_pk_fma_f32 v[172:173], v[156:157], v[164:165], v[172:173]
	v_pk_fma_f32 v[174:175], v[158:159], v[166:167], v[174:175]
	v_pk_mul_f32 v[160:161], v[168:169], s[36:37]
	v_pk_mul_f32 v[162:163], v[170:171], s[36:37]
	v_pk_mul_f32 v[164:165], v[172:173], s[36:37]
	v_pk_mul_f32 v[166:167], v[174:175], s[36:37]
	v_exp_f32_e32 v160, v160
	v_exp_f32_e32 v161, v161
	v_exp_f32_e32 v162, v162
	v_exp_f32_e32 v163, v163
	v_exp_f32_e32 v164, v164
	v_exp_f32_e32 v165, v165
	v_exp_f32_e32 v166, v166
	v_exp_f32_e32 v167, v167
	v_pk_add_f32 v[160:161], v[160:161], s[38:39]
	v_pk_add_f32 v[162:163], v[162:163], s[38:39]
	v_pk_add_f32 v[164:165], v[164:165], s[38:39]
	v_pk_add_f32 v[166:167], v[166:167], s[38:39]
	v_rcp_f32_e32 v160, v160
	v_rcp_f32_e32 v161, v161
	v_rcp_f32_e32 v162, v162
	v_rcp_f32_e32 v163, v163
	v_rcp_f32_e32 v164, v164
	v_rcp_f32_e32 v165, v165
	v_rcp_f32_e32 v166, v166
	v_rcp_f32_e32 v167, v167
	v_pk_mul_f32 v[168:169], v[168:169], v[160:161]
	v_pk_mul_f32 v[170:171], v[170:171], v[162:163]
	v_pk_mul_f32 v[172:173], v[172:173], v[164:165]
	v_pk_mul_f32 v[174:175], v[174:175], v[166:167]
	v_pk_mul_f32 v[160:161], v[168:169], v[168:169]
	v_pk_fma_f32 v[160:161], v[170:171], v[170:171], v[160:161]
	v_pk_fma_f32 v[160:161], v[172:173], v[172:173], v[160:161]
	v_pk_fma_f32 v[160:161], v[174:175], v[174:175], v[160:161]
	s_nop 0
	v_add_f32_e32 v162, v160, v161
	s_nop 1
	v_add_f32_dpp v162, v162, v162 quad_perm:[1,0,3,2] row_mask:0xf bank_mask:0xf
	s_nop 1
	v_add_f32_dpp v162, v162, v162 quad_perm:[2,3,0,1] row_mask:0xf bank_mask:0xf
	s_nop 1
	v_add_f32_dpp v162, v162, v162 row_half_mirror row_mask:0xf bank_mask:0xf
	s_nop 1
	v_add_f32_dpp v162, v162, v162 row_mirror row_mask:0xf bank_mask:0xf
	v_add_f32_e32 v162, 0x358637bd, v162
	v_rsq_f32_e32 v162, v162
	s_nop 0
	v_pk_mul_f32 v[168:169], v[168:169], v[162:163] op_sel_hi:[1,0]
	v_pk_mul_f32 v[170:171], v[170:171], v[162:163] op_sel_hi:[1,0]
	v_pk_mul_f32 v[172:173], v[172:173], v[162:163] op_sel_hi:[1,0]
	v_pk_mul_f32 v[174:175], v[174:175], v[162:163] op_sel_hi:[1,0]
	v_cvt_pk_bf16_f32 v20, v168, v169
	v_cvt_pk_bf16_f32 v21, v170, v171
	v_cvt_pk_bf16_f32 v22, v172, v173
	v_cvt_pk_bf16_f32 v23, v174, v175
	v_lshlrev_b32_e32 v160, 16, v96
	v_and_b32_e32 v161, 0xffff0000, v96
	v_lshlrev_b32_e32 v162, 16, v97
	v_and_b32_e32 v163, 0xffff0000, v97
	v_lshlrev_b32_e32 v164, 16, v98
	v_and_b32_e32 v165, 0xffff0000, v98
	v_lshlrev_b32_e32 v166, 16, v99
	v_and_b32_e32 v167, 0xffff0000, v99
	v_pk_mul_f32 v[168:169], v[128:129], v[160:161]
	v_pk_mul_f32 v[170:171], v[130:131], v[162:163]
	v_pk_mul_f32 v[172:173], v[132:133], v[164:165]
	v_pk_mul_f32 v[174:175], v[134:135], v[166:167]
	v_lshlrev_b32_e32 v160, 16, v100
	v_and_b32_e32 v161, 0xffff0000, v100
	v_lshlrev_b32_e32 v162, 16, v101
	v_and_b32_e32 v163, 0xffff0000, v101
	v_lshlrev_b32_e32 v164, 16, v102
	v_and_b32_e32 v165, 0xffff0000, v102
	v_lshlrev_b32_e32 v166, 16, v103
	v_and_b32_e32 v167, 0xffff0000, v103
	v_pk_fma_f32 v[168:169], v[136:137], v[160:161], v[168:169]
	v_pk_fma_f32 v[170:171], v[138:139], v[162:163], v[170:171]
	v_pk_fma_f32 v[172:173], v[140:141], v[164:165], v[172:173]
	v_pk_fma_f32 v[174:175], v[142:143], v[166:167], v[174:175]
	v_lshlrev_b32_e32 v160, 16, v104
	v_and_b32_e32 v161, 0xffff0000, v104
	v_lshlrev_b32_e32 v162, 16, v105
	v_and_b32_e32 v163, 0xffff0000, v105
	v_lshlrev_b32_e32 v164, 16, v106
	v_and_b32_e32 v165, 0xffff0000, v106
	v_lshlrev_b32_e32 v166, 16, v107
	v_and_b32_e32 v167, 0xffff0000, v107
	v_pk_fma_f32 v[168:169], v[144:145], v[160:161], v[168:169]
	v_pk_fma_f32 v[170:171], v[146:147], v[162:163], v[170:171]
	v_pk_fma_f32 v[172:173], v[148:149], v[164:165], v[172:173]
	v_pk_fma_f32 v[174:175], v[150:151], v[166:167], v[174:175]
	v_lshlrev_b32_e32 v160, 16, v108
	v_and_b32_e32 v161, 0xffff0000, v108
	v_lshlrev_b32_e32 v162, 16, v109
	v_and_b32_e32 v163, 0xffff0000, v109
	v_lshlrev_b32_e32 v164, 16, v110
	v_and_b32_e32 v165, 0xffff0000, v110
	v_lshlrev_b32_e32 v166, 16, v111
	v_and_b32_e32 v167, 0xffff0000, v111
	v_pk_fma_f32 v[168:169], v[152:153], v[160:161], v[168:169]
	v_pk_fma_f32 v[170:171], v[154:155], v[162:163], v[170:171]
	v_pk_fma_f32 v[172:173], v[156:157], v[164:165], v[172:173]
	v_pk_fma_f32 v[174:175], v[158:159], v[166:167], v[174:175]
	v_pk_mul_f32 v[160:161], v[168:169], s[36:37]
	v_pk_mul_f32 v[162:163], v[170:171], s[36:37]
	v_pk_mul_f32 v[164:165], v[172:173], s[36:37]
	v_pk_mul_f32 v[166:167], v[174:175], s[36:37]
	v_exp_f32_e32 v160, v160
	v_exp_f32_e32 v161, v161
	v_exp_f32_e32 v162, v162
	v_exp_f32_e32 v163, v163
	v_exp_f32_e32 v164, v164
	v_exp_f32_e32 v165, v165
	v_exp_f32_e32 v166, v166
	v_exp_f32_e32 v167, v167
	v_pk_add_f32 v[160:161], v[160:161], s[38:39]
	v_pk_add_f32 v[162:163], v[162:163], s[38:39]
	v_pk_add_f32 v[164:165], v[164:165], s[38:39]
	v_pk_add_f32 v[166:167], v[166:167], s[38:39]
	v_rcp_f32_e32 v160, v160
	v_rcp_f32_e32 v161, v161
	v_rcp_f32_e32 v162, v162
	v_rcp_f32_e32 v163, v163
	v_rcp_f32_e32 v164, v164
	v_rcp_f32_e32 v165, v165
	v_rcp_f32_e32 v166, v166
	v_rcp_f32_e32 v167, v167
	v_pk_mul_f32 v[168:169], v[168:169], v[160:161]
	v_pk_mul_f32 v[170:171], v[170:171], v[162:163]
	v_pk_mul_f32 v[172:173], v[172:173], v[164:165]
	v_pk_mul_f32 v[174:175], v[174:175], v[166:167]
; __device__ __forceinline__ unsigned pk2(float lo, float hi) { const f32v2_t v = {lo, hi}; const bf16v2_t b = __builtin_convertvector(v, bf16v2_t); return __builtin_bit_cast(unsigned, b); }
; __device__ __forceinline__ float lo16(unsigned u) { return __uint_as_float(u << 16); }
; __device__ __forceinline__ float hi16(unsigned u) { return __uint_as_float(u & 0xffff0000u); }
; __device__ __forceinline__ float siluf_(float x) { return x * __builtin_amdgcn_rcpf(1.0f + __expf(-x)); }
; __device__ __forceinline__ void prep_dn_load(const bf16_t* proj, const float* cw, int idx, u32x4 (&raw)[4], int& t, int& ch) {
;     if (idx >= 0) { t = idx / 384; const int j = idx - t * 384; ch = j * 8; }
; #pragma unroll
;     for (int k = 0; k < 4; ++k) { const int tt = t - 3 + k; raw[k] = (u32x4){0u, 0u, 0u, 0u};
;         if (tt >= 0) raw[k] = *(const u32x4*)(proj + (size_t)tt * NP + C_DNQ + ch); }
; }
; __device__ __forceinline__ void prep_dn_finish(const float* cw, bf16_t* dq, bf16_t* dk, bf16_t* dv, const u32x4 (&raw)[4], int t, int ch) {
;     float a[8];
; #pragma unroll
;     for (int e = 0; e < 8; ++e) a[e] = 0.f;
; #pragma unroll
;     for (int k = 0; k < 4; ++k) {
;         const f32x4 w0 = *(const f32x4*)(cw + k * 3072 + ch), w1 = *(const f32x4*)(cw + k * 3072 + ch + 4);
;         a[0] += w0[0] * lo16(raw[k].x); a[1] += w0[1] * hi16(raw[k].x); a[2] += w0[2] * lo16(raw[k].y); a[3] += w0[3] * hi16(raw[k].y);
;         a[4] += w1[0] * lo16(raw[k].z); a[5] += w1[1] * hi16(raw[k].z); a[6] += w1[2] * lo16(raw[k].w); a[7] += w1[3] * hi16(raw[k].w); }
;     float ss = 0.f;
; #pragma unroll
;     for (int e = 0; e < 8; ++e) { a[e] = siluf_(a[e]); ss += a[e] * a[e]; }
;     ss += __shfl_xor(ss, 1); ss += __shfl_xor(ss, 2); ss += __shfl_xor(ss, 4); ss += __shfl_xor(ss, 8);
;     float sc = 1.0f;
;     if (ch < 2048) { sc = rsqrtf(ss + EPS); if (ch < 1024) sc *= 0.08838834764831845f; }
;     u32x4 w; w.x = pk2(a[0] * sc, a[1] * sc); w.y = pk2(a[2] * sc, a[3] * sc); w.z = pk2(a[4] * sc, a[5] * sc); w.w = pk2(a[6] * sc, a[7] * sc);
	v_pk_mul_f32 v[160:161], v[168:169], v[168:169]
	v_pk_fma_f32 v[160:161], v[170:171], v[170:171], v[160:161]
	v_pk_fma_f32 v[160:161], v[172:173], v[172:173], v[160:161]
	v_pk_fma_f32 v[160:161], v[174:175], v[174:175], v[160:161]
	s_nop 0
	v_add_f32_e32 v162, v160, v161
	s_nop 1
	v_add_f32_dpp v162, v162, v162 quad_perm:[1,0,3,2] row_mask:0xf bank_mask:0xf
	s_nop 1
	v_add_f32_dpp v162, v162, v162 quad_perm:[2,3,0,1] row_mask:0xf bank_mask:0xf
	s_nop 1
	v_add_f32_dpp v162, v162, v162 row_half_mirror row_mask:0xf bank_mask:0xf
	s_nop 1
	v_add_f32_dpp v162, v162, v162 row_mirror row_mask:0xf bank_mask:0xf
	v_add_f32_e32 v162, 0x358637bd, v162
	v_rsq_f32_e32 v162, v162
	s_nop 0
	v_pk_mul_f32 v[168:169], v[168:169], v[162:163] op_sel_hi:[1,0]
	v_pk_mul_f32 v[170:171], v[170:171], v[162:163] op_sel_hi:[1,0]
	v_pk_mul_f32 v[172:173], v[172:173], v[162:163] op_sel_hi:[1,0]
	v_pk_mul_f32 v[174:175], v[174:175], v[162:163] op_sel_hi:[1,0]
	v_cvt_pk_bf16_f32 v24, v168, v169
	v_cvt_pk_bf16_f32 v25, v170, v171
	v_cvt_pk_bf16_f32 v26, v172, v173
	v_cvt_pk_bf16_f32 v27, v174, v175
	v_lshlrev_b32_e32 v160, 16, v112
	v_and_b32_e32 v161, 0xffff0000, v112
	v_lshlrev_b32_e32 v162, 16, v113
	v_and_b32_e32 v163, 0xffff0000, v113
	v_lshlrev_b32_e32 v164, 16, v114
	v_and_b32_e32 v165, 0xffff0000, v114
	v_lshlrev_b32_e32 v166, 16, v115
	v_and_b32_e32 v167, 0xffff0000, v115
	v_pk_mul_f32 v[168:169], v[128:129], v[160:161]
	v_pk_mul_f32 v[170:171], v[130:131], v[162:163]
	v_pk_mul_f32 v[172:173], v[132:133], v[164:165]
	v_pk_mul_f32 v[174:175], v[134:135], v[166:167]
	v_lshlrev_b32_e32 v160, 16, v116
	v_and_b32_e32 v161, 0xffff0000, v116
	v_lshlrev_b32_e32 v162, 16, v117
	v_and_b32_e32 v163, 0xffff0000, v117
	v_lshlrev_b32_e32 v164, 16, v118
	v_and_b32_e32 v165, 0xffff0000, v118
	v_lshlrev_b32_e32 v166, 16, v119
	v_and_b32_e32 v167, 0xffff0000, v119
	v_pk_fma_f32 v[168:169], v[136:137], v[160:161], v[168:169]
	v_pk_fma_f32 v[170:171], v[138:139], v[162:163], v[170:171]
	v_pk_fma_f32 v[172:173], v[140:141], v[164:165], v[172:173]
	v_pk_fma_f32 v[174:175], v[142:143], v[166:167], v[174:175]
	v_lshlrev_b32_e32 v160, 16, v120
	v_and_b32_e32 v161, 0xffff0000, v120
	v_lshlrev_b32_e32 v162, 16, v121
	v_and_b32_e32 v163, 0xffff0000, v121
	v_lshlrev_b32_e32 v164, 16, v122
	v_and_b32_e32 v165, 0xffff0000, v122
	v_lshlrev_b32_e32 v166, 16, v123
	v_and_b32_e32 v167, 0xffff0000, v123
	v_pk_fma_f32 v[168:169], v[144:145], v[160:161], v[168:169]
	v_pk_fma_f32 v[170:171], v[146:147], v[162:163], v[170:171]
	v_pk_fma_f32 v[172:173], v[148:149], v[164:165], v[172:173]
	v_pk_fma_f32 v[174:175], v[150:151], v[166:167], v[174:175]
	v_lshlrev_b32_e32 v160, 16, v124
	v_and_b32_e32 v161, 0xffff0000, v124
	v_lshlrev_b32_e32 v162, 16, v125
	v_and_b32_e32 v163, 0xffff0000, v125
	v_lshlrev_b32_e32 v164, 16, v126
	v_and_b32_e32 v165, 0xffff0000, v126
	v_lshlrev_b32_e32 v166, 16, v127
	v_and_b32_e32 v167, 0xffff0000, v127
	v_pk_fma_f32 v[168:169], v[152:153], v[160:161], v[168:169]
	v_pk_fma_f32 v[170:171], v[154:155], v[162:163], v[170:171]
	v_pk_fma_f32 v[172:173], v[156:157], v[164:165], v[172:173]
	v_pk_fma_f32 v[174:175], v[158:159], v[166:167], v[174:175]
	v_pk_mul_f32 v[160:161], v[168:169], s[36:37]
	v_pk_mul_f32 v[162:163], v[170:171], s[36:37]
	v_pk_mul_f32 v[164:165], v[172:173], s[36:37]
	v_pk_mul_f32 v[166:167], v[174:175], s[36:37]
	v_exp_f32_e32 v160, v160
	v_exp_f32_e32 v161, v161
	v_exp_f32_e32 v162, v162
	v_exp_f32_e32 v163, v163
	v_exp_f32_e32 v164, v164
	v_exp_f32_e32 v165, v165
	v_exp_f32_e32 v166, v166
	v_exp_f32_e32 v167, v167
	v_pk_add_f32 v[160:161], v[160:161], s[38:39]
	v_pk_add_f32 v[162:163], v[162:163], s[38:39]
	v_pk_add_f32 v[164:165], v[164:165], s[38:39]
	v_pk_add_f32 v[166:167], v[166:167], s[38:39]
	v_rcp_f32_e32 v160, v160
	v_rcp_f32_e32 v161, v161
	v_rcp_f32_e32 v162, v162
	v_rcp_f32_e32 v163, v163
	v_rcp_f32_e32 v164, v164
	v_rcp_f32_e32 v165, v165
	v_rcp_f32_e32 v166, v166
	v_rcp_f32_e32 v167, v167
	v_pk_mul_f32 v[168:169], v[168:169], v[160:161]
	v_pk_mul_f32 v[170:171], v[170:171], v[162:163]
	v_pk_mul_f32 v[172:173], v[172:173], v[164:165]
	v_pk_mul_f32 v[174:175], v[174:175], v[166:167]
	v_pk_mul_f32 v[160:161], v[168:169], v[168:169]
	v_pk_fma_f32 v[160:161], v[170:171], v[170:171], v[160:161]
	v_pk_fma_f32 v[160:161], v[172:173], v[172:173], v[160:161]
	v_pk_fma_f32 v[160:161], v[174:175], v[174:175], v[160:161]
	s_nop 0
	v_add_f32_e32 v162, v160, v161
	s_nop 1
	v_add_f32_dpp v162, v162, v162 quad_perm:[1,0,3,2] row_mask:0xf bank_mask:0xf
	s_nop 1
	v_add_f32_dpp v162, v162, v162 quad_perm:[2,3,0,1] row_mask:0xf bank_mask:0xf
	s_nop 1
	v_add_f32_dpp v162, v162, v162 row_half_mirror row_mask:0xf bank_mask:0xf
	s_nop 1
	v_add_f32_dpp v162, v162, v162 row_mirror row_mask:0xf bank_mask:0xf
	v_add_f32_e32 v162, 0x358637bd, v162
	v_rsq_f32_e32 v162, v162
	s_nop 0
	v_pk_mul_f32 v[168:169], v[168:169], v[162:163] op_sel_hi:[1,0]
	v_pk_mul_f32 v[170:171], v[170:171], v[162:163] op_sel_hi:[1,0]
	v_pk_mul_f32 v[172:173], v[172:173], v[162:163] op_sel_hi:[1,0]
	v_pk_mul_f32 v[174:175], v[174:175], v[162:163] op_sel_hi:[1,0]
	v_cvt_pk_bf16_f32 v28, v168, v169
	v_cvt_pk_bf16_f32 v29, v170, v171
	v_cvt_pk_bf16_f32 v30, v172, v173
	v_cvt_pk_bf16_f32 v31, v174, v175
	s_add_u32 vcc_lo, s40, 0x2000
	s_addc_u32 vcc_hi, s41, 0
	global_load_dwordx4 v[128:131], v15, vcc
	global_load_dwordx4 v[132:135], v15, vcc offset:16
	s_add_u32 vcc_lo, s40, 0x5000
	s_addc_u32 vcc_hi, s41, 0
	global_load_dwordx4 v[136:139], v15, vcc
	global_load_dwordx4 v[140:143], v15, vcc offset:16
	s_add_u32 vcc_lo, s40, 0x8000
	s_addc_u32 vcc_hi, s41, 0
	global_load_dwordx4 v[144:147], v15, vcc
; __device__ __forceinline__ unsigned pk2(float lo, float hi) { const f32v2_t v = {lo, hi}; const bf16v2_t b = __builtin_convertvector(v, bf16v2_t); return __builtin_bit_cast(unsigned, b); }
; __device__ __forceinline__ float lo16(unsigned u) { return __uint_as_float(u << 16); }
; __device__ __forceinline__ float hi16(unsigned u) { return __uint_as_float(u & 0xffff0000u); }
; __device__ __forceinline__ float siluf_(float x) { return x * __builtin_amdgcn_rcpf(1.0f + __expf(-x)); }
; __device__ __forceinline__ void prep_dn_load(const bf16_t* proj, const float* cw, int idx, u32x4 (&raw)[4], int& t, int& ch) {
;     if (idx >= 0) { t = idx / 384; const int j = idx - t * 384; ch = j * 8; }
; #pragma unroll
;     for (int k = 0; k < 4; ++k) { const int tt = t - 3 + k; raw[k] = (u32x4){0u, 0u, 0u, 0u};
;         if (tt >= 0) raw[k] = *(const u32x4*)(proj + (size_t)tt * NP + C_DNQ + ch); }
; }
; __device__ __forceinline__ void prep_dn_finish(const float* cw, bf16_t* dq, bf16_t* dk, bf16_t* dv, const u32x4 (&raw)[4], int t, int ch) {
;     float a[8];
; #pragma unroll
;     for (int e = 0; e < 8; ++e) a[e] = 0.f;
; #pragma unroll
;     for (int k = 0; k < 4; ++k) {
;         const f32x4 w0 = *(const f32x4*)(cw + k * 3072 + ch), w1 = *(const f32x4*)(cw + k * 3072 + ch + 4);
;         a[0] += w0[0] * lo16(raw[k].x); a[1] += w0[1] * hi16(raw[k].x); a[2] += w0[2] * lo16(raw[k].y); a[3] += w0[3] * hi16(raw[k].y);
;         a[4] += w1[0] * lo16(raw[k].z); a[5] += w1[1] * hi16(raw[k].z); a[6] += w1[2] * lo16(raw[k].w); a[7] += w1[3] * hi16(raw[k].w); }
;     float ss = 0.f;
; #pragma unroll
;     for (int e = 0; e < 8; ++e) { a[e] = siluf_(a[e]); ss += a[e] * a[e]; }
;     ss += __shfl_xor(ss, 1); ss += __shfl_xor(ss, 2); ss += __shfl_xor(ss, 4); ss += __shfl_xor(ss, 8);
;     float sc = 1.0f;
;     if (ch < 2048) { sc = rsqrtf(ss + EPS); if (ch < 1024) sc *= 0.08838834764831845f; }
;     u32x4 w; w.x = pk2(a[0] * sc, a[1] * sc); w.y = pk2(a[2] * sc, a[3] * sc); w.z = pk2(a[4] * sc, a[5] * sc); w.w = pk2(a[6] * sc, a[7] * sc);
	global_load_dwordx4 v[148:151], v15, vcc offset:16
	s_add_u32 vcc_lo, s40, 0xb000
	s_addc_u32 vcc_hi, s41, 0
	global_load_dwordx4 v[152:155], v15, vcc
	global_load_dwordx4 v[156:159], v15, vcc offset:16
	s_add_u32 s22, s4, 0x9be9600
	s_addc_u32 s23, s5, 0
	global_load_dwordx4 v[64:67], v14, s[22:23]
	s_add_u32 s22, s4, 0x9bf1400
	s_addc_u32 s23, s5, 0
	global_load_dwordx4 v[68:71], v14, s[22:23]
	s_add_u32 s22, s4, 0x9bf9200
	s_addc_u32 s23, s5, 0
	global_load_dwordx4 v[72:75], v14, s[22:23]
	s_add_u32 s22, s4, 0x9c01000
	s_addc_u32 s23, s5, 0
	global_load_dwordx4 v[76:79], v14, s[22:23]
	s_add_u32 s22, s4, 0x9c67600
	s_addc_u32 s23, s5, 0
	global_load_dwordx4 v[80:83], v14, s[22:23]
	s_add_u32 s22, s4, 0x9c6f400
	s_addc_u32 s23, s5, 0
	global_load_dwordx4 v[84:87], v14, s[22:23]
	s_add_u32 s22, s4, 0x9c77200
	s_addc_u32 s23, s5, 0
	global_load_dwordx4 v[88:91], v14, s[22:23]
	s_add_u32 s22, s4, 0x9c7f000
	s_addc_u32 s23, s5, 0
	global_load_dwordx4 v[92:95], v14, s[22:23]
	s_add_u32 s22, s4, 0x9ce5600
	s_addc_u32 s23, s5, 0
	global_load_dwordx4 v[96:99], v14, s[22:23]
	s_add_u32 s22, s4, 0x9ced400
	s_addc_u32 s23, s5, 0
	global_load_dwordx4 v[100:103], v14, s[22:23]
	s_add_u32 s22, s4, 0x9cf5200
	s_addc_u32 s23, s5, 0
	global_load_dwordx4 v[104:107], v14, s[22:23]
	s_add_u32 s22, s4, 0x9cfd000
	s_addc_u32 s23, s5, 0
	global_load_dwordx4 v[108:111], v14, s[22:23]
	s_add_u32 s22, s4, 0x9d63600
	s_addc_u32 s23, s5, 0
	global_load_dwordx4 v[112:115], v14, s[22:23]
	s_add_u32 s22, s4, 0x9d6b400
	s_addc_u32 s23, s5, 0
	global_load_dwordx4 v[116:119], v14, s[22:23]
	s_add_u32 s22, s4, 0x9d73200
	s_addc_u32 s23, s5, 0
	global_load_dwordx4 v[120:123], v14, s[22:23]
	s_add_u32 s22, s4, 0x9d7b000
	s_addc_u32 s23, s5, 0
	global_load_dwordx4 v[124:127], v14, s[22:23]
	s_waitcnt vmcnt(0)
	s_cmp_lg_u32 s7, 0
	s_cbranch_scc1 .Ldnd_nz1
	v_mov_b32_e32 v13, 0
	v_cmp_gt_u32_e32 vcc, 3, v12
	v_cndmask_b32_e32 v64, v64, v13, vcc
	v_cndmask_b32_e32 v65, v65, v13, vcc
	v_cndmask_b32_e32 v66, v66, v13, vcc
	v_cndmask_b32_e32 v67, v67, v13, vcc
	v_cmp_gt_u32_e32 vcc, 2, v12
	v_cndmask_b32_e32 v68, v68, v13, vcc
	v_cndmask_b32_e32 v69, v69, v13, vcc
	v_cndmask_b32_e32 v70, v70, v13, vcc
	v_cndmask_b32_e32 v71, v71, v13, vcc
	v_cmp_gt_u32_e32 vcc, 1, v12
	v_cndmask_b32_e32 v72, v72, v13, vcc
	v_cndmask_b32_e32 v73, v73, v13, vcc
	v_cndmask_b32_e32 v74, v74, v13, vcc
	v_cndmask_b32_e32 v75, v75, v13, vcc
.Ldnd_nz1:
	v_lshlrev_b32_e32 v160, 16, v64
	v_and_b32_e32 v161, 0xffff0000, v64
	v_lshlrev_b32_e32 v162, 16, v65
	v_and_b32_e32 v163, 0xffff0000, v65
	v_lshlrev_b32_e32 v164, 16, v66
	v_and_b32_e32 v165, 0xffff0000, v66
	v_lshlrev_b32_e32 v166, 16, v67
	v_and_b32_e32 v167, 0xffff0000, v67
	v_pk_mul_f32 v[168:169], v[128:129], v[160:161]
	v_pk_mul_f32 v[170:171], v[130:131], v[162:163]
	v_pk_mul_f32 v[172:173], v[132:133], v[164:165]
	v_pk_mul_f32 v[174:175], v[134:135], v[166:167]
	v_lshlrev_b32_e32 v160, 16, v68
	v_and_b32_e32 v161, 0xffff0000, v68
	v_lshlrev_b32_e32 v162, 16, v69
	v_and_b32_e32 v163, 0xffff0000, v69
	v_lshlrev_b32_e32 v164, 16, v70
	v_and_b32_e32 v165, 0xffff0000, v70
	v_lshlrev_b32_e32 v166, 16, v71
	v_and_b32_e32 v167, 0xffff0000, v71
	v_pk_fma_f32 v[168:169], v[136:137], v[160:161], v[168:169]
	v_pk_fma_f32 v[170:171], v[138:139], v[162:163], v[170:171]
	v_pk_fma_f32 v[172:173], v[140:141], v[164:165], v[172:173]
	v_pk_fma_f32 v[174:175], v[142:143], v[166:167], v[174:175]
	v_lshlrev_b32_e32 v160, 16, v72
	v_and_b32_e32 v161, 0xffff0000, v72
	v_lshlrev_b32_e32 v162, 16, v73
	v_and_b32_e32 v163, 0xffff0000, v73
	v_lshlrev_b32_e32 v164, 16, v74
	v_and_b32_e32 v165, 0xffff0000, v74
	v_lshlrev_b32_e32 v166, 16, v75
	v_and_b32_e32 v167, 0xffff0000, v75
	v_pk_fma_f32 v[168:169], v[144:145], v[160:161], v[168:169]
	v_pk_fma_f32 v[170:171], v[146:147], v[162:163], v[170:171]
	v_pk_fma_f32 v[172:173], v[148:149], v[164:165], v[172:173]
	v_pk_fma_f32 v[174:175], v[150:151], v[166:167], v[174:175]
	v_lshlrev_b32_e32 v160, 16, v76
	v_and_b32_e32 v161, 0xffff0000, v76
	v_lshlrev_b32_e32 v162, 16, v77
	v_and_b32_e32 v163, 0xffff0000, v77
	v_lshlrev_b32_e32 v164, 16, v78
	v_and_b32_e32 v165, 0xffff0000, v78
	v_lshlrev_b32_e32 v166, 16, v79
	v_and_b32_e32 v167, 0xffff0000, v79
	v_pk_fma_f32 v[168:169], v[152:153], v[160:161], v[168:169]
	v_pk_fma_f32 v[170:171], v[154:155], v[162:163], v[170:171]
	v_pk_fma_f32 v[172:173], v[156:157], v[164:165], v[172:173]
	v_pk_fma_f32 v[174:175], v[158:159], v[166:167], v[174:175]
	v_pk_mul_f32 v[160:161], v[168:169], s[36:37]
	v_pk_mul_f32 v[162:163], v[170:171], s[36:37]
	v_pk_mul_f32 v[164:165], v[172:173], s[36:37]
	v_pk_mul_f32 v[166:167], v[174:175], s[36:37]
	v_exp_f32_e32 v160, v160
	v_exp_f32_e32 v161, v161
	v_exp_f32_e32 v162, v162
	v_exp_f32_e32 v163, v163
	v_exp_f32_e32 v164, v164
	v_exp_f32_e32 v165, v165
	v_exp_f32_e32 v166, v166
	v_exp_f32_e32 v167, v167
	v_pk_add_f32 v[160:161], v[160:161], s[38:39]
	v_pk_add_f32 v[162:163], v[162:163], s[38:39]
	v_pk_add_f32 v[164:165], v[164:165], s[38:39]
	v_pk_add_f32 v[166:167], v[166:167], s[38:39]
	v_rcp_f32_e32 v160, v160
	v_rcp_f32_e32 v161, v161
	v_rcp_f32_e32 v162, v162
	v_rcp_f32_e32 v163, v163
	v_rcp_f32_e32 v164, v164
	v_rcp_f32_e32 v165, v165
	v_rcp_f32_e32 v166, v166
	v_rcp_f32_e32 v167, v167
	v_pk_mul_f32 v[168:169], v[168:169], v[160:161]
	v_pk_mul_f32 v[170:171], v[170:171], v[162:163]
	v_pk_mul_f32 v[172:173], v[172:173], v[164:165]
	v_pk_mul_f32 v[174:175], v[174:175], v[166:167]
	v_cvt_pk_bf16_f32 v32, v168, v169
	v_cvt_pk_bf16_f32 v33, v170, v171
	v_cvt_pk_bf16_f32 v34, v172, v173
	v_cvt_pk_bf16_f32 v35, v174, v175
	v_lshlrev_b32_e32 v160, 16, v80
; __device__ __forceinline__ unsigned pk2(float lo, float hi) { const f32v2_t v = {lo, hi}; const bf16v2_t b = __builtin_convertvector(v, bf16v2_t); return __builtin_bit_cast(unsigned, b); }
; __device__ __forceinline__ float lo16(unsigned u) { return __uint_as_float(u << 16); }
; __device__ __forceinline__ float hi16(unsigned u) { return __uint_as_float(u & 0xffff0000u); }
; __device__ __forceinline__ float siluf_(float x) { return x * __builtin_amdgcn_rcpf(1.0f + __expf(-x)); }
; __device__ __forceinline__ void prep_dn_finish(const float* cw, bf16_t* dq, bf16_t* dk, bf16_t* dv, const u32x4 (&raw)[4], int t, int ch) {
;     float a[8];
; #pragma unroll
;     for (int e = 0; e < 8; ++e) a[e] = 0.f;
; #pragma unroll
;     for (int k = 0; k < 4; ++k) {
;         const f32x4 w0 = *(const f32x4*)(cw + k * 3072 + ch), w1 = *(const f32x4*)(cw + k * 3072 + ch + 4);
;         a[0] += w0[0] * lo16(raw[k].x); a[1] += w0[1] * hi16(raw[k].x); a[2] += w0[2] * lo16(raw[k].y); a[3] += w0[3] * hi16(raw[k].y);
;         a[4] += w1[0] * lo16(raw[k].z); a[5] += w1[1] * hi16(raw[k].z); a[6] += w1[2] * lo16(raw[k].w); a[7] += w1[3] * hi16(raw[k].w); }
;     float ss = 0.f;
; #pragma unroll
;     for (int e = 0; e < 8; ++e) { a[e] = siluf_(a[e]); ss += a[e] * a[e]; }
;     ss += __shfl_xor(ss, 1); ss += __shfl_xor(ss, 2); ss += __shfl_xor(ss, 4); ss += __shfl_xor(ss, 8);
;     float sc = 1.0f;
;     if (ch < 2048) { sc = rsqrtf(ss + EPS); if (ch < 1024) sc *= 0.08838834764831845f; }
;     u32x4 w; w.x = pk2(a[0] * sc, a[1] * sc); w.y = pk2(a[2] * sc, a[3] * sc); w.z = pk2(a[4] * sc, a[5] * sc); w.w = pk2(a[6] * sc, a[7] * sc);
	v_and_b32_e32 v161, 0xffff0000, v80
	v_lshlrev_b32_e32 v162, 16, v81
	v_and_b32_e32 v163, 0xffff0000, v81
	v_lshlrev_b32_e32 v164, 16, v82
	v_and_b32_e32 v165, 0xffff0000, v82
	v_lshlrev_b32_e32 v166, 16, v83
	v_and_b32_e32 v167, 0xffff0000, v83
	v_pk_mul_f32 v[168:169], v[128:129], v[160:161]
	v_pk_mul_f32 v[170:171], v[130:131], v[162:163]
	v_pk_mul_f32 v[172:173], v[132:133], v[164:165]
	v_pk_mul_f32 v[174:175], v[134:135], v[166:167]
	v_lshlrev_b32_e32 v160, 16, v84
	v_and_b32_e32 v161, 0xffff0000, v84
	v_lshlrev_b32_e32 v162, 16, v85
	v_and_b32_e32 v163, 0xffff0000, v85
	v_lshlrev_b32_e32 v164, 16, v86
	v_and_b32_e32 v165, 0xffff0000, v86
	v_lshlrev_b32_e32 v166, 16, v87
	v_and_b32_e32 v167, 0xffff0000, v87
	v_pk_fma_f32 v[168:169], v[136:137], v[160:161], v[168:169]
	v_pk_fma_f32 v[170:171], v[138:139], v[162:163], v[170:171]
	v_pk_fma_f32 v[172:173], v[140:141], v[164:165], v[172:173]
	v_pk_fma_f32 v[174:175], v[142:143], v[166:167], v[174:175]
	v_lshlrev_b32_e32 v160, 16, v88
	v_and_b32_e32 v161, 0xffff0000, v88
	v_lshlrev_b32_e32 v162, 16, v89
	v_and_b32_e32 v163, 0xffff0000, v89
	v_lshlrev_b32_e32 v164, 16, v90
	v_and_b32_e32 v165, 0xffff0000, v90
	v_lshlrev_b32_e32 v166, 16, v91
	v_and_b32_e32 v167, 0xffff0000, v91
	v_pk_fma_f32 v[168:169], v[144:145], v[160:161], v[168:169]
	v_pk_fma_f32 v[170:171], v[146:147], v[162:163], v[170:171]
	v_pk_fma_f32 v[172:173], v[148:149], v[164:165], v[172:173]
	v_pk_fma_f32 v[174:175], v[150:151], v[166:167], v[174:175]
	v_lshlrev_b32_e32 v160, 16, v92
	v_and_b32_e32 v161, 0xffff0000, v92
	v_lshlrev_b32_e32 v162, 16, v93
	v_and_b32_e32 v163, 0xffff0000, v93
	v_lshlrev_b32_e32 v164, 16, v94
	v_and_b32_e32 v165, 0xffff0000, v94
	v_lshlrev_b32_e32 v166, 16, v95
	v_and_b32_e32 v167, 0xffff0000, v95
	v_pk_fma_f32 v[168:169], v[152:153], v[160:161], v[168:169]
	v_pk_fma_f32 v[170:171], v[154:155], v[162:163], v[170:171]
	v_pk_fma_f32 v[172:173], v[156:157], v[164:165], v[172:173]
	v_pk_fma_f32 v[174:175], v[158:159], v[166:167], v[174:175]
	v_pk_mul_f32 v[160:161], v[168:169], s[36:37]
	v_pk_mul_f32 v[162:163], v[170:171], s[36:37]
	v_pk_mul_f32 v[164:165], v[172:173], s[36:37]
	v_pk_mul_f32 v[166:167], v[174:175], s[36:37]
	v_exp_f32_e32 v160, v160
	v_exp_f32_e32 v161, v161
	v_exp_f32_e32 v162, v162
	v_exp_f32_e32 v163, v163
	v_exp_f32_e32 v164, v164
	v_exp_f32_e32 v165, v165
	v_exp_f32_e32 v166, v166
	v_exp_f32_e32 v167, v167
	v_pk_add_f32 v[160:161], v[160:161], s[38:39]
	v_pk_add_f32 v[162:163], v[162:163], s[38:39]
	v_pk_add_f32 v[164:165], v[164:165], s[38:39]
	v_pk_add_f32 v[166:167], v[166:167], s[38:39]
	v_rcp_f32_e32 v160, v160
	v_rcp_f32_e32 v161, v161
	v_rcp_f32_e32 v162, v162
	v_rcp_f32_e32 v163, v163
	v_rcp_f32_e32 v164, v164
	v_rcp_f32_e32 v165, v165
	v_rcp_f32_e32 v166, v166
	v_rcp_f32_e32 v167, v167
	v_pk_mul_f32 v[168:169], v[168:169], v[160:161]
	v_pk_mul_f32 v[170:171], v[170:171], v[162:163]
	v_pk_mul_f32 v[172:173], v[172:173], v[164:165]
	v_pk_mul_f32 v[174:175], v[174:175], v[166:167]
	v_cvt_pk_bf16_f32 v36, v168, v169
	v_cvt_pk_bf16_f32 v37, v170, v171
	v_cvt_pk_bf16_f32 v38, v172, v173
	v_cvt_pk_bf16_f32 v39, v174, v175
	v_lshlrev_b32_e32 v160, 16, v96
	v_and_b32_e32 v161, 0xffff0000, v96
	v_lshlrev_b32_e32 v162, 16, v97
	v_and_b32_e32 v163, 0xffff0000, v97
	v_lshlrev_b32_e32 v164, 16, v98
	v_and_b32_e32 v165, 0xffff0000, v98
	v_lshlrev_b32_e32 v166, 16, v99
	v_and_b32_e32 v167, 0xffff0000, v99
	v_pk_mul_f32 v[168:169], v[128:129], v[160:161]
	v_pk_mul_f32 v[170:171], v[130:131], v[162:163]
	v_pk_mul_f32 v[172:173], v[132:133], v[164:165]
	v_pk_mul_f32 v[174:175], v[134:135], v[166:167]
	v_lshlrev_b32_e32 v160, 16, v100
	v_and_b32_e32 v161, 0xffff0000, v100
	v_lshlrev_b32_e32 v162, 16, v101
	v_and_b32_e32 v163, 0xffff0000, v101
	v_lshlrev_b32_e32 v164, 16, v102
	v_and_b32_e32 v165, 0xffff0000, v102
	v_lshlrev_b32_e32 v166, 16, v103
	v_and_b32_e32 v167, 0xffff0000, v103
	v_pk_fma_f32 v[168:169], v[136:137], v[160:161], v[168:169]
	v_pk_fma_f32 v[170:171], v[138:139], v[162:163], v[170:171]
	v_pk_fma_f32 v[172:173], v[140:141], v[164:165], v[172:173]
	v_pk_fma_f32 v[174:175], v[142:143], v[166:167], v[174:175]
	v_lshlrev_b32_e32 v160, 16, v104
	v_and_b32_e32 v161, 0xffff0000, v104
	v_lshlrev_b32_e32 v162, 16, v105
	v_and_b32_e32 v163, 0xffff0000, v105
	v_lshlrev_b32_e32 v164, 16, v106
	v_and_b32_e32 v165, 0xffff0000, v106
	v_lshlrev_b32_e32 v166, 16, v107
	v_and_b32_e32 v167, 0xffff0000, v107
	v_pk_fma_f32 v[168:169], v[144:145], v[160:161], v[168:169]
	v_pk_fma_f32 v[170:171], v[146:147], v[162:163], v[170:171]
	v_pk_fma_f32 v[172:173], v[148:149], v[164:165], v[172:173]
	v_pk_fma_f32 v[174:175], v[150:151], v[166:167], v[174:175]
	v_lshlrev_b32_e32 v160, 16, v108
	v_and_b32_e32 v161, 0xffff0000, v108
	v_lshlrev_b32_e32 v162, 16, v109
	v_and_b32_e32 v163, 0xffff0000, v109
	v_lshlrev_b32_e32 v164, 16, v110
	v_and_b32_e32 v165, 0xffff0000, v110
	v_lshlrev_b32_e32 v166, 16, v111
	v_and_b32_e32 v167, 0xffff0000, v111
	v_pk_fma_f32 v[168:169], v[152:153], v[160:161], v[168:169]
	v_pk_fma_f32 v[170:171], v[154:155], v[162:163], v[170:171]
	v_pk_fma_f32 v[172:173], v[156:157], v[164:165], v[172:173]
	v_pk_fma_f32 v[174:175], v[158:159], v[166:167], v[174:175]
	v_pk_mul_f32 v[160:161], v[168:169], s[36:37]
	v_pk_mul_f32 v[162:163], v[170:171], s[36:37]
	v_pk_mul_f32 v[164:165], v[172:173], s[36:37]
	v_pk_mul_f32 v[166:167], v[174:175], s[36:37]
	v_exp_f32_e32 v160, v160
	v_exp_f32_e32 v161, v161
	v_exp_f32_e32 v162, v162
	v_exp_f32_e32 v163, v163
	v_exp_f32_e32 v164, v164
	v_exp_f32_e32 v165, v165
	v_exp_f32_e32 v166, v166
	v_exp_f32_e32 v167, v167
	v_pk_add_f32 v[160:161], v[160:161], s[38:39]
; __device__ __forceinline__ unsigned pk2(float lo, float hi) { const f32v2_t v = {lo, hi}; const bf16v2_t b = __builtin_convertvector(v, bf16v2_t); return __builtin_bit_cast(unsigned, b); }
; __device__ __forceinline__ float lo16(unsigned u) { return __uint_as_float(u << 16); }
; __device__ __forceinline__ float hi16(unsigned u) { return __uint_as_float(u & 0xffff0000u); }
; __device__ __forceinline__ float siluf_(float x) { return x * __builtin_amdgcn_rcpf(1.0f + __expf(-x)); }
; __device__ __forceinline__ void prep_dn_load(const bf16_t* proj, const float* cw, int idx, u32x4 (&raw)[4], int& t, int& ch) {
;     if (idx >= 0) { t = idx / 384; const int j = idx - t * 384; ch = j * 8; }
; #pragma unroll
;     for (int k = 0; k < 4; ++k) { const int tt = t - 3 + k; raw[k] = (u32x4){0u, 0u, 0u, 0u};
;         if (tt >= 0) raw[k] = *(const u32x4*)(proj + (size_t)tt * NP + C_DNQ + ch); }
; }
; __device__ __forceinline__ void prep_dn_finish(const float* cw, bf16_t* dq, bf16_t* dk, bf16_t* dv, const u32x4 (&raw)[4], int t, int ch) {
;     float a[8];
; #pragma unroll
;     for (int e = 0; e < 8; ++e) a[e] = 0.f;
; #pragma unroll
;     for (int k = 0; k < 4; ++k) {
;         const f32x4 w0 = *(const f32x4*)(cw + k * 3072 + ch), w1 = *(const f32x4*)(cw + k * 3072 + ch + 4);
;         a[0] += w0[0] * lo16(raw[k].x); a[1] += w0[1] * hi16(raw[k].x); a[2] += w0[2] * lo16(raw[k].y); a[3] += w0[3] * hi16(raw[k].y);
;         a[4] += w1[0] * lo16(raw[k].z); a[5] += w1[1] * hi16(raw[k].z); a[6] += w1[2] * lo16(raw[k].w); a[7] += w1[3] * hi16(raw[k].w); }
;     float ss = 0.f;
; #pragma unroll
;     for (int e = 0; e < 8; ++e) { a[e] = siluf_(a[e]); ss += a[e] * a[e]; }
;     ss += __shfl_xor(ss, 1); ss += __shfl_xor(ss, 2); ss += __shfl_xor(ss, 4); ss += __shfl_xor(ss, 8);
;     float sc = 1.0f;
;     if (ch < 2048) { sc = rsqrtf(ss + EPS); if (ch < 1024) sc *= 0.08838834764831845f; }
;     u32x4 w; w.x = pk2(a[0] * sc, a[1] * sc); w.y = pk2(a[2] * sc, a[3] * sc); w.z = pk2(a[4] * sc, a[5] * sc); w.w = pk2(a[6] * sc, a[7] * sc);
	v_pk_add_f32 v[162:163], v[162:163], s[38:39]
	v_pk_add_f32 v[164:165], v[164:165], s[38:39]
	v_pk_add_f32 v[166:167], v[166:167], s[38:39]
	v_rcp_f32_e32 v160, v160
	v_rcp_f32_e32 v161, v161
	v_rcp_f32_e32 v162, v162
	v_rcp_f32_e32 v163, v163
	v_rcp_f32_e32 v164, v164
	v_rcp_f32_e32 v165, v165
	v_rcp_f32_e32 v166, v166
	v_rcp_f32_e32 v167, v167
	v_pk_mul_f32 v[168:169], v[168:169], v[160:161]
	v_pk_mul_f32 v[170:171], v[170:171], v[162:163]
	v_pk_mul_f32 v[172:173], v[172:173], v[164:165]
	v_pk_mul_f32 v[174:175], v[174:175], v[166:167]
	v_cvt_pk_bf16_f32 v40, v168, v169
	v_cvt_pk_bf16_f32 v41, v170, v171
	v_cvt_pk_bf16_f32 v42, v172, v173
	v_cvt_pk_bf16_f32 v43, v174, v175
	v_lshlrev_b32_e32 v160, 16, v112
	v_and_b32_e32 v161, 0xffff0000, v112
	v_lshlrev_b32_e32 v162, 16, v113
	v_and_b32_e32 v163, 0xffff0000, v113
	v_lshlrev_b32_e32 v164, 16, v114
	v_and_b32_e32 v165, 0xffff0000, v114
	v_lshlrev_b32_e32 v166, 16, v115
	v_and_b32_e32 v167, 0xffff0000, v115
	v_pk_mul_f32 v[168:169], v[128:129], v[160:161]
	v_pk_mul_f32 v[170:171], v[130:131], v[162:163]
	v_pk_mul_f32 v[172:173], v[132:133], v[164:165]
	v_pk_mul_f32 v[174:175], v[134:135], v[166:167]
	v_lshlrev_b32_e32 v160, 16, v116
	v_and_b32_e32 v161, 0xffff0000, v116
	v_lshlrev_b32_e32 v162, 16, v117
	v_and_b32_e32 v163, 0xffff0000, v117
	v_lshlrev_b32_e32 v164, 16, v118
	v_and_b32_e32 v165, 0xffff0000, v118
	v_lshlrev_b32_e32 v166, 16, v119
	v_and_b32_e32 v167, 0xffff0000, v119
	v_pk_fma_f32 v[168:169], v[136:137], v[160:161], v[168:169]
	v_pk_fma_f32 v[170:171], v[138:139], v[162:163], v[170:171]
	v_pk_fma_f32 v[172:173], v[140:141], v[164:165], v[172:173]
	v_pk_fma_f32 v[174:175], v[142:143], v[166:167], v[174:175]
	v_lshlrev_b32_e32 v160, 16, v120
	v_and_b32_e32 v161, 0xffff0000, v120
	v_lshlrev_b32_e32 v162, 16, v121
	v_and_b32_e32 v163, 0xffff0000, v121
	v_lshlrev_b32_e32 v164, 16, v122
	v_and_b32_e32 v165, 0xffff0000, v122
	v_lshlrev_b32_e32 v166, 16, v123
	v_and_b32_e32 v167, 0xffff0000, v123
	v_pk_fma_f32 v[168:169], v[144:145], v[160:161], v[168:169]
	v_pk_fma_f32 v[170:171], v[146:147], v[162:163], v[170:171]
	v_pk_fma_f32 v[172:173], v[148:149], v[164:165], v[172:173]
	v_pk_fma_f32 v[174:175], v[150:151], v[166:167], v[174:175]
	v_lshlrev_b32_e32 v160, 16, v124
	v_and_b32_e32 v161, 0xffff0000, v124
	v_lshlrev_b32_e32 v162, 16, v125
	v_and_b32_e32 v163, 0xffff0000, v125
	v_lshlrev_b32_e32 v164, 16, v126
	v_and_b32_e32 v165, 0xffff0000, v126
	v_lshlrev_b32_e32 v166, 16, v127
	v_and_b32_e32 v167, 0xffff0000, v127
	v_pk_fma_f32 v[168:169], v[152:153], v[160:161], v[168:169]
	v_pk_fma_f32 v[170:171], v[154:155], v[162:163], v[170:171]
	v_pk_fma_f32 v[172:173], v[156:157], v[164:165], v[172:173]
	v_pk_fma_f32 v[174:175], v[158:159], v[166:167], v[174:175]
	v_pk_mul_f32 v[160:161], v[168:169], s[36:37]
	v_pk_mul_f32 v[162:163], v[170:171], s[36:37]
	v_pk_mul_f32 v[164:165], v[172:173], s[36:37]
	v_pk_mul_f32 v[166:167], v[174:175], s[36:37]
	v_exp_f32_e32 v160, v160
	v_exp_f32_e32 v161, v161
	v_exp_f32_e32 v162, v162
	v_exp_f32_e32 v163, v163
	v_exp_f32_e32 v164, v164
	v_exp_f32_e32 v165, v165
	v_exp_f32_e32 v166, v166
	v_exp_f32_e32 v167, v167
	v_pk_add_f32 v[160:161], v[160:161], s[38:39]
	v_pk_add_f32 v[162:163], v[162:163], s[38:39]
	v_pk_add_f32 v[164:165], v[164:165], s[38:39]
	v_pk_add_f32 v[166:167], v[166:167], s[38:39]
	v_rcp_f32_e32 v160, v160
	v_rcp_f32_e32 v161, v161
	v_rcp_f32_e32 v162, v162
	v_rcp_f32_e32 v163, v163
	v_rcp_f32_e32 v164, v164
	v_rcp_f32_e32 v165, v165
	v_rcp_f32_e32 v166, v166
	v_rcp_f32_e32 v167, v167
	v_pk_mul_f32 v[168:169], v[168:169], v[160:161]
	v_pk_mul_f32 v[170:171], v[170:171], v[162:163]
	v_pk_mul_f32 v[172:173], v[172:173], v[164:165]
	v_pk_mul_f32 v[174:175], v[174:175], v[166:167]
	v_cvt_pk_bf16_f32 v44, v168, v169
	v_cvt_pk_bf16_f32 v45, v170, v171
	v_cvt_pk_bf16_f32 v46, v172, v173
	v_cvt_pk_bf16_f32 v47, v174, v175
	s_add_u32 vcc_lo, s40, 0x0
	s_addc_u32 vcc_hi, s41, 0
	global_load_dwordx4 v[128:131], v15, vcc
	global_load_dwordx4 v[132:135], v15, vcc offset:16
	s_add_u32 vcc_lo, s40, 0x3000
	s_addc_u32 vcc_hi, s41, 0
	global_load_dwordx4 v[136:139], v15, vcc
	global_load_dwordx4 v[140:143], v15, vcc offset:16
	s_add_u32 vcc_lo, s40, 0x6000
	s_addc_u32 vcc_hi, s41, 0
	global_load_dwordx4 v[144:147], v15, vcc
	global_load_dwordx4 v[148:151], v15, vcc offset:16
	s_add_u32 vcc_lo, s40, 0x9000
	s_addc_u32 vcc_hi, s41, 0
	global_load_dwordx4 v[152:155], v15, vcc
	global_load_dwordx4 v[156:159], v15, vcc offset:16
	s_add_u32 s22, s4, 0x9be8600
	s_addc_u32 s23, s5, 0
	global_load_dwordx4 v[64:67], v14, s[22:23]
	s_add_u32 s22, s4, 0x9bf0400
	s_addc_u32 s23, s5, 0
	global_load_dwordx4 v[68:71], v14, s[22:23]
	s_add_u32 s22, s4, 0x9bf8200
	s_addc_u32 s23, s5, 0
	global_load_dwordx4 v[72:75], v14, s[22:23]
	s_add_u32 s22, s4, 0x9c00000
	s_addc_u32 s23, s5, 0
	global_load_dwordx4 v[76:79], v14, s[22:23]
	s_add_u32 s22, s4, 0x9c66600
	s_addc_u32 s23, s5, 0
	global_load_dwordx4 v[80:83], v14, s[22:23]
	s_add_u32 s22, s4, 0x9c6e400
	s_addc_u32 s23, s5, 0
	global_load_dwordx4 v[84:87], v14, s[22:23]
	s_add_u32 s22, s4, 0x9c76200
	s_addc_u32 s23, s5, 0
	global_load_dwordx4 v[88:91], v14, s[22:23]
	s_add_u32 s22, s4, 0x9c7e000
	s_addc_u32 s23, s5, 0
	global_load_dwordx4 v[92:95], v14, s[22:23]
	s_add_u32 s22, s4, 0x9ce4600
	s_addc_u32 s23, s5, 0
	global_load_dwordx4 v[96:99], v14, s[22:23]
	s_add_u32 s22, s4, 0x9cec400
	s_addc_u32 s23, s5, 0
	global_load_dwordx4 v[100:103], v14, s[22:23]
	s_add_u32 s22, s4, 0x9cf4200
	s_addc_u32 s23, s5, 0
	global_load_dwordx4 v[104:107], v14, s[22:23]
	s_add_u32 s22, s4, 0x9cfc000
	s_addc_u32 s23, s5, 0
	global_load_dwordx4 v[108:111], v14, s[22:23]
	s_add_u32 s22, s4, 0x9d62600
	s_addc_u32 s23, s5, 0
	global_load_dwordx4 v[112:115], v14, s[22:23]
	s_add_u32 s22, s4, 0x9d6a400
	s_addc_u32 s23, s5, 0
	global_load_dwordx4 v[116:119], v14, s[22:23]
	s_add_u32 s22, s4, 0x9d72200
	s_addc_u32 s23, s5, 0
	global_load_dwordx4 v[120:123], v14, s[22:23]
	s_add_u32 s22, s4, 0x9d7a000
	s_addc_u32 s23, s5, 0
	global_load_dwordx4 v[124:127], v14, s[22:23]
	s_waitcnt vmcnt(0)
	s_cmp_lg_u32 s7, 0
	s_cbranch_scc1 .Ldnd_nz2
	v_mov_b32_e32 v13, 0
	v_cmp_gt_u32_e32 vcc, 3, v12
	v_cndmask_b32_e32 v64, v64, v13, vcc
	v_cndmask_b32_e32 v65, v65, v13, vcc
	v_cndmask_b32_e32 v66, v66, v13, vcc
	v_cndmask_b32_e32 v67, v67, v13, vcc
	v_cmp_gt_u32_e32 vcc, 2, v12
	v_cndmask_b32_e32 v68, v68, v13, vcc
	v_cndmask_b32_e32 v69, v69, v13, vcc
	v_cndmask_b32_e32 v70, v70, v13, vcc
	v_cndmask_b32_e32 v71, v71, v13, vcc
	v_cmp_gt_u32_e32 vcc, 1, v12
	v_cndmask_b32_e32 v72, v72, v13, vcc
	v_cndmask_b32_e32 v73, v73, v13, vcc
	v_cndmask_b32_e32 v74, v74, v13, vcc
	v_cndmask_b32_e32 v75, v75, v13, vcc
; __device__ __forceinline__ unsigned pk2(float lo, float hi) { const f32v2_t v = {lo, hi}; const bf16v2_t b = __builtin_convertvector(v, bf16v2_t); return __builtin_bit_cast(unsigned, b); }
; __device__ __forceinline__ float lo16(unsigned u) { return __uint_as_float(u << 16); }
; __device__ __forceinline__ float hi16(unsigned u) { return __uint_as_float(u & 0xffff0000u); }
; __device__ __forceinline__ float siluf_(float x) { return x * __builtin_amdgcn_rcpf(1.0f + __expf(-x)); }
; __device__ __forceinline__ void prep_dn_finish(const float* cw, bf16_t* dq, bf16_t* dk, bf16_t* dv, const u32x4 (&raw)[4], int t, int ch) {
;     float a[8];
; #pragma unroll
;     for (int e = 0; e < 8; ++e) a[e] = 0.f;
; #pragma unroll
;     for (int k = 0; k < 4; ++k) {
;         const f32x4 w0 = *(const f32x4*)(cw + k * 3072 + ch), w1 = *(const f32x4*)(cw + k * 3072 + ch + 4);
;         a[0] += w0[0] * lo16(raw[k].x); a[1] += w0[1] * hi16(raw[k].x); a[2] += w0[2] * lo16(raw[k].y); a[3] += w0[3] * hi16(raw[k].y);
;         a[4] += w1[0] * lo16(raw[k].z); a[5] += w1[1] * hi16(raw[k].z); a[6] += w1[2] * lo16(raw[k].w); a[7] += w1[3] * hi16(raw[k].w); }
;     float ss = 0.f;
; #pragma unroll
;     for (int e = 0; e < 8; ++e) { a[e] = siluf_(a[e]); ss += a[e] * a[e]; }
;     ss += __shfl_xor(ss, 1); ss += __shfl_xor(ss, 2); ss += __shfl_xor(ss, 4); ss += __shfl_xor(ss, 8);
;     float sc = 1.0f;
;     if (ch < 2048) { sc = rsqrtf(ss + EPS); if (ch < 1024) sc *= 0.08838834764831845f; }
;     u32x4 w; w.x = pk2(a[0] * sc, a[1] * sc); w.y = pk2(a[2] * sc, a[3] * sc); w.z = pk2(a[4] * sc, a[5] * sc); w.w = pk2(a[6] * sc, a[7] * sc);
;     bf16_t* dst = (ch < 1024) ? dq : (ch < 2048 ? dk : dv);
;     *(u32x4*)(dst + (size_t)t * 1024 + (ch & 1023)) = w;
.Ldnd_nz2:
	v_lshlrev_b32_e32 v160, 16, v64
	v_and_b32_e32 v161, 0xffff0000, v64
	v_lshlrev_b32_e32 v162, 16, v65
	v_and_b32_e32 v163, 0xffff0000, v65
	v_lshlrev_b32_e32 v164, 16, v66
	v_and_b32_e32 v165, 0xffff0000, v66
	v_lshlrev_b32_e32 v166, 16, v67
	v_and_b32_e32 v167, 0xffff0000, v67
	v_pk_mul_f32 v[168:169], v[128:129], v[160:161]
	v_pk_mul_f32 v[170:171], v[130:131], v[162:163]
	v_pk_mul_f32 v[172:173], v[132:133], v[164:165]
	v_pk_mul_f32 v[174:175], v[134:135], v[166:167]
	v_lshlrev_b32_e32 v160, 16, v68
	v_and_b32_e32 v161, 0xffff0000, v68
	v_lshlrev_b32_e32 v162, 16, v69
	v_and_b32_e32 v163, 0xffff0000, v69
	v_lshlrev_b32_e32 v164, 16, v70
	v_and_b32_e32 v165, 0xffff0000, v70
	v_lshlrev_b32_e32 v166, 16, v71
	v_and_b32_e32 v167, 0xffff0000, v71
	v_pk_fma_f32 v[168:169], v[136:137], v[160:161], v[168:169]
	v_pk_fma_f32 v[170:171], v[138:139], v[162:163], v[170:171]
	v_pk_fma_f32 v[172:173], v[140:141], v[164:165], v[172:173]
	v_pk_fma_f32 v[174:175], v[142:143], v[166:167], v[174:175]
	v_lshlrev_b32_e32 v160, 16, v72
	v_and_b32_e32 v161, 0xffff0000, v72
	v_lshlrev_b32_e32 v162, 16, v73
	v_and_b32_e32 v163, 0xffff0000, v73
	v_lshlrev_b32_e32 v164, 16, v74
	v_and_b32_e32 v165, 0xffff0000, v74
	v_lshlrev_b32_e32 v166, 16, v75
	v_and_b32_e32 v167, 0xffff0000, v75
	v_pk_fma_f32 v[168:169], v[144:145], v[160:161], v[168:169]
	v_pk_fma_f32 v[170:171], v[146:147], v[162:163], v[170:171]
	v_pk_fma_f32 v[172:173], v[148:149], v[164:165], v[172:173]
	v_pk_fma_f32 v[174:175], v[150:151], v[166:167], v[174:175]
	v_lshlrev_b32_e32 v160, 16, v76
	v_and_b32_e32 v161, 0xffff0000, v76
	v_lshlrev_b32_e32 v162, 16, v77
	v_and_b32_e32 v163, 0xffff0000, v77
	v_lshlrev_b32_e32 v164, 16, v78
	v_and_b32_e32 v165, 0xffff0000, v78
	v_lshlrev_b32_e32 v166, 16, v79
	v_and_b32_e32 v167, 0xffff0000, v79
	v_pk_fma_f32 v[168:169], v[152:153], v[160:161], v[168:169]
	v_pk_fma_f32 v[170:171], v[154:155], v[162:163], v[170:171]
	v_pk_fma_f32 v[172:173], v[156:157], v[164:165], v[172:173]
	v_pk_fma_f32 v[174:175], v[158:159], v[166:167], v[174:175]
	v_pk_mul_f32 v[160:161], v[168:169], s[36:37]
	v_pk_mul_f32 v[162:163], v[170:171], s[36:37]
	v_pk_mul_f32 v[164:165], v[172:173], s[36:37]
	v_pk_mul_f32 v[166:167], v[174:175], s[36:37]
	v_exp_f32_e32 v160, v160
	v_exp_f32_e32 v161, v161
	v_exp_f32_e32 v162, v162
	v_exp_f32_e32 v163, v163
	v_exp_f32_e32 v164, v164
	v_exp_f32_e32 v165, v165
	v_exp_f32_e32 v166, v166
	v_exp_f32_e32 v167, v167
	v_pk_add_f32 v[160:161], v[160:161], s[38:39]
	v_pk_add_f32 v[162:163], v[162:163], s[38:39]
	v_pk_add_f32 v[164:165], v[164:165], s[38:39]
	v_pk_add_f32 v[166:167], v[166:167], s[38:39]
	v_rcp_f32_e32 v160, v160
	v_rcp_f32_e32 v161, v161
	v_rcp_f32_e32 v162, v162
	v_rcp_f32_e32 v163, v163
	v_rcp_f32_e32 v164, v164
	v_rcp_f32_e32 v165, v165
	v_rcp_f32_e32 v166, v166
	v_rcp_f32_e32 v167, v167
	v_pk_mul_f32 v[168:169], v[168:169], v[160:161]
	v_pk_mul_f32 v[170:171], v[170:171], v[162:163]
	v_pk_mul_f32 v[172:173], v[172:173], v[164:165]
	v_pk_mul_f32 v[174:175], v[174:175], v[166:167]
	v_pk_mul_f32 v[160:161], v[168:169], v[168:169]
	v_pk_fma_f32 v[160:161], v[170:171], v[170:171], v[160:161]
	v_pk_fma_f32 v[160:161], v[172:173], v[172:173], v[160:161]
	v_pk_fma_f32 v[160:161], v[174:175], v[174:175], v[160:161]
	s_nop 0
	v_add_f32_e32 v162, v160, v161
	s_nop 1
	v_add_f32_dpp v162, v162, v162 quad_perm:[1,0,3,2] row_mask:0xf bank_mask:0xf
	s_nop 1
	v_add_f32_dpp v162, v162, v162 quad_perm:[2,3,0,1] row_mask:0xf bank_mask:0xf
	s_nop 1
	v_add_f32_dpp v162, v162, v162 row_half_mirror row_mask:0xf bank_mask:0xf
	s_nop 1
	v_add_f32_dpp v162, v162, v162 row_mirror row_mask:0xf bank_mask:0xf
	v_add_f32_e32 v162, 0x358637bd, v162
	v_rsq_f32_e32 v162, v162
	s_nop 0
	v_mul_f32_e32 v162, 0x3db504f3, v162
	v_pk_mul_f32 v[168:169], v[168:169], v[162:163] op_sel_hi:[1,0]
	v_pk_mul_f32 v[170:171], v[170:171], v[162:163] op_sel_hi:[1,0]
	v_pk_mul_f32 v[172:173], v[172:173], v[162:163] op_sel_hi:[1,0]
	v_pk_mul_f32 v[174:175], v[174:175], v[162:163] op_sel_hi:[1,0]
	v_cvt_pk_bf16_f32 v48, v168, v169
	v_cvt_pk_bf16_f32 v49, v170, v171
	v_cvt_pk_bf16_f32 v50, v172, v173
	v_cvt_pk_bf16_f32 v51, v174, v175
	v_add_u32_e32 v13, 0x1f100000, v5
	global_store_dwordx4 v13, v[48:51], s[4:5]
	v_lshlrev_b32_e32 v160, 16, v80
	v_and_b32_e32 v161, 0xffff0000, v80
	v_lshlrev_b32_e32 v162, 16, v81
	v_and_b32_e32 v163, 0xffff0000, v81
	v_lshlrev_b32_e32 v164, 16, v82
	v_and_b32_e32 v165, 0xffff0000, v82
	v_lshlrev_b32_e32 v166, 16, v83
	v_and_b32_e32 v167, 0xffff0000, v83
	v_pk_mul_f32 v[168:169], v[128:129], v[160:161]
	v_pk_mul_f32 v[170:171], v[130:131], v[162:163]
	v_pk_mul_f32 v[172:173], v[132:133], v[164:165]
	v_pk_mul_f32 v[174:175], v[134:135], v[166:167]
	v_lshlrev_b32_e32 v160, 16, v84
	v_and_b32_e32 v161, 0xffff0000, v84
	v_lshlrev_b32_e32 v162, 16, v85
	v_and_b32_e32 v163, 0xffff0000, v85
	v_lshlrev_b32_e32 v164, 16, v86
	v_and_b32_e32 v165, 0xffff0000, v86
	v_lshlrev_b32_e32 v166, 16, v87
	v_and_b32_e32 v167, 0xffff0000, v87
	v_pk_fma_f32 v[168:169], v[136:137], v[160:161], v[168:169]
	v_pk_fma_f32 v[170:171], v[138:139], v[162:163], v[170:171]
	v_pk_fma_f32 v[172:173], v[140:141], v[164:165], v[172:173]
	v_pk_fma_f32 v[174:175], v[142:143], v[166:167], v[174:175]
	v_lshlrev_b32_e32 v160, 16, v88
	v_and_b32_e32 v161, 0xffff0000, v88
	v_lshlrev_b32_e32 v162, 16, v89
	v_and_b32_e32 v163, 0xffff0000, v89
	v_lshlrev_b32_e32 v164, 16, v90
	v_and_b32_e32 v165, 0xffff0000, v90
	v_lshlrev_b32_e32 v166, 16, v91
	v_and_b32_e32 v167, 0xffff0000, v91
	v_pk_fma_f32 v[168:169], v[144:145], v[160:161], v[168:169]
	v_pk_fma_f32 v[170:171], v[146:147], v[162:163], v[170:171]
; __device__ __forceinline__ unsigned pk2(float lo, float hi) { const f32v2_t v = {lo, hi}; const bf16v2_t b = __builtin_convertvector(v, bf16v2_t); return __builtin_bit_cast(unsigned, b); }
; __device__ __forceinline__ float lo16(unsigned u) { return __uint_as_float(u << 16); }
; __device__ __forceinline__ float hi16(unsigned u) { return __uint_as_float(u & 0xffff0000u); }
; __device__ __forceinline__ float siluf_(float x) { return x * __builtin_amdgcn_rcpf(1.0f + __expf(-x)); }
; __device__ __forceinline__ void prep_dn_finish(const float* cw, bf16_t* dq, bf16_t* dk, bf16_t* dv, const u32x4 (&raw)[4], int t, int ch) {
;     float a[8];
; #pragma unroll
;     for (int e = 0; e < 8; ++e) a[e] = 0.f;
; #pragma unroll
;     for (int k = 0; k < 4; ++k) {
;         const f32x4 w0 = *(const f32x4*)(cw + k * 3072 + ch), w1 = *(const f32x4*)(cw + k * 3072 + ch + 4);
;         a[0] += w0[0] * lo16(raw[k].x); a[1] += w0[1] * hi16(raw[k].x); a[2] += w0[2] * lo16(raw[k].y); a[3] += w0[3] * hi16(raw[k].y);
;         a[4] += w1[0] * lo16(raw[k].z); a[5] += w1[1] * hi16(raw[k].z); a[6] += w1[2] * lo16(raw[k].w); a[7] += w1[3] * hi16(raw[k].w); }
;     float ss = 0.f;
; #pragma unroll
;     for (int e = 0; e < 8; ++e) { a[e] = siluf_(a[e]); ss += a[e] * a[e]; }
;     ss += __shfl_xor(ss, 1); ss += __shfl_xor(ss, 2); ss += __shfl_xor(ss, 4); ss += __shfl_xor(ss, 8);
;     float sc = 1.0f;
;     if (ch < 2048) { sc = rsqrtf(ss + EPS); if (ch < 1024) sc *= 0.08838834764831845f; }
;     u32x4 w; w.x = pk2(a[0] * sc, a[1] * sc); w.y = pk2(a[2] * sc, a[3] * sc); w.z = pk2(a[4] * sc, a[5] * sc); w.w = pk2(a[6] * sc, a[7] * sc);
;     bf16_t* dst = (ch < 1024) ? dq : (ch < 2048 ? dk : dv);
;     *(u32x4*)(dst + (size_t)t * 1024 + (ch & 1023)) = w;
	v_pk_fma_f32 v[172:173], v[148:149], v[164:165], v[172:173]
	v_pk_fma_f32 v[174:175], v[150:151], v[166:167], v[174:175]
	v_lshlrev_b32_e32 v160, 16, v92
	v_and_b32_e32 v161, 0xffff0000, v92
	v_lshlrev_b32_e32 v162, 16, v93
	v_and_b32_e32 v163, 0xffff0000, v93
	v_lshlrev_b32_e32 v164, 16, v94
	v_and_b32_e32 v165, 0xffff0000, v94
	v_lshlrev_b32_e32 v166, 16, v95
	v_and_b32_e32 v167, 0xffff0000, v95
	v_pk_fma_f32 v[168:169], v[152:153], v[160:161], v[168:169]
	v_pk_fma_f32 v[170:171], v[154:155], v[162:163], v[170:171]
	v_pk_fma_f32 v[172:173], v[156:157], v[164:165], v[172:173]
	v_pk_fma_f32 v[174:175], v[158:159], v[166:167], v[174:175]
	v_pk_mul_f32 v[160:161], v[168:169], s[36:37]
	v_pk_mul_f32 v[162:163], v[170:171], s[36:37]
	v_pk_mul_f32 v[164:165], v[172:173], s[36:37]
	v_pk_mul_f32 v[166:167], v[174:175], s[36:37]
	v_exp_f32_e32 v160, v160
	v_exp_f32_e32 v161, v161
	v_exp_f32_e32 v162, v162
	v_exp_f32_e32 v163, v163
	v_exp_f32_e32 v164, v164
	v_exp_f32_e32 v165, v165
	v_exp_f32_e32 v166, v166
	v_exp_f32_e32 v167, v167
	v_pk_add_f32 v[160:161], v[160:161], s[38:39]
	v_pk_add_f32 v[162:163], v[162:163], s[38:39]
	v_pk_add_f32 v[164:165], v[164:165], s[38:39]
	v_pk_add_f32 v[166:167], v[166:167], s[38:39]
	v_rcp_f32_e32 v160, v160
	v_rcp_f32_e32 v161, v161
	v_rcp_f32_e32 v162, v162
	v_rcp_f32_e32 v163, v163
	v_rcp_f32_e32 v164, v164
	v_rcp_f32_e32 v165, v165
	v_rcp_f32_e32 v166, v166
	v_rcp_f32_e32 v167, v167
	v_pk_mul_f32 v[168:169], v[168:169], v[160:161]
	v_pk_mul_f32 v[170:171], v[170:171], v[162:163]
	v_pk_mul_f32 v[172:173], v[172:173], v[164:165]
	v_pk_mul_f32 v[174:175], v[174:175], v[166:167]
	v_pk_mul_f32 v[160:161], v[168:169], v[168:169]
	v_pk_fma_f32 v[160:161], v[170:171], v[170:171], v[160:161]
	v_pk_fma_f32 v[160:161], v[172:173], v[172:173], v[160:161]
	v_pk_fma_f32 v[160:161], v[174:175], v[174:175], v[160:161]
	s_nop 0
	v_add_f32_e32 v162, v160, v161
	s_nop 1
	v_add_f32_dpp v162, v162, v162 quad_perm:[1,0,3,2] row_mask:0xf bank_mask:0xf
	s_nop 1
	v_add_f32_dpp v162, v162, v162 quad_perm:[2,3,0,1] row_mask:0xf bank_mask:0xf
	s_nop 1
	v_add_f32_dpp v162, v162, v162 row_half_mirror row_mask:0xf bank_mask:0xf
	s_nop 1
	v_add_f32_dpp v162, v162, v162 row_mirror row_mask:0xf bank_mask:0xf
	v_add_f32_e32 v162, 0x358637bd, v162
	v_rsq_f32_e32 v162, v162
	s_nop 0
	v_mul_f32_e32 v162, 0x3db504f3, v162
	v_pk_mul_f32 v[168:169], v[168:169], v[162:163] op_sel_hi:[1,0]
	v_pk_mul_f32 v[170:171], v[170:171], v[162:163] op_sel_hi:[1,0]
	v_pk_mul_f32 v[172:173], v[172:173], v[162:163] op_sel_hi:[1,0]
	v_pk_mul_f32 v[174:175], v[174:175], v[162:163] op_sel_hi:[1,0]
	v_cvt_pk_bf16_f32 v52, v168, v169
	v_cvt_pk_bf16_f32 v53, v170, v171
	v_cvt_pk_bf16_f32 v54, v172, v173
	v_cvt_pk_bf16_f32 v55, v174, v175
	v_add_u32_e32 v13, 0x1f108000, v5
	global_store_dwordx4 v13, v[52:55], s[4:5]
	v_lshlrev_b32_e32 v160, 16, v96
	v_and_b32_e32 v161, 0xffff0000, v96
	v_lshlrev_b32_e32 v162, 16, v97
	v_and_b32_e32 v163, 0xffff0000, v97
	v_lshlrev_b32_e32 v164, 16, v98
	v_and_b32_e32 v165, 0xffff0000, v98
	v_lshlrev_b32_e32 v166, 16, v99
	v_and_b32_e32 v167, 0xffff0000, v99
	v_pk_mul_f32 v[168:169], v[128:129], v[160:161]
	v_pk_mul_f32 v[170:171], v[130:131], v[162:163]
	v_pk_mul_f32 v[172:173], v[132:133], v[164:165]
	v_pk_mul_f32 v[174:175], v[134:135], v[166:167]
	v_lshlrev_b32_e32 v160, 16, v100
	v_and_b32_e32 v161, 0xffff0000, v100
	v_lshlrev_b32_e32 v162, 16, v101
	v_and_b32_e32 v163, 0xffff0000, v101
	v_lshlrev_b32_e32 v164, 16, v102
	v_and_b32_e32 v165, 0xffff0000, v102
	v_lshlrev_b32_e32 v166, 16, v103
	v_and_b32_e32 v167, 0xffff0000, v103
	v_pk_fma_f32 v[168:169], v[136:137], v[160:161], v[168:169]
	v_pk_fma_f32 v[170:171], v[138:139], v[162:163], v[170:171]
	v_pk_fma_f32 v[172:173], v[140:141], v[164:165], v[172:173]
	v_pk_fma_f32 v[174:175], v[142:143], v[166:167], v[174:175]
	v_lshlrev_b32_e32 v160, 16, v104
	v_and_b32_e32 v161, 0xffff0000, v104
	v_lshlrev_b32_e32 v162, 16, v105
	v_and_b32_e32 v163, 0xffff0000, v105
	v_lshlrev_b32_e32 v164, 16, v106
	v_and_b32_e32 v165, 0xffff0000, v106
	v_lshlrev_b32_e32 v166, 16, v107
	v_and_b32_e32 v167, 0xffff0000, v107
	v_pk_fma_f32 v[168:169], v[144:145], v[160:161], v[168:169]
	v_pk_fma_f32 v[170:171], v[146:147], v[162:163], v[170:171]
	v_pk_fma_f32 v[172:173], v[148:149], v[164:165], v[172:173]
	v_pk_fma_f32 v[174:175], v[150:151], v[166:167], v[174:175]
	v_lshlrev_b32_e32 v160, 16, v108
	v_and_b32_e32 v161, 0xffff0000, v108
	v_lshlrev_b32_e32 v162, 16, v109
	v_and_b32_e32 v163, 0xffff0000, v109
	v_lshlrev_b32_e32 v164, 16, v110
	v_and_b32_e32 v165, 0xffff0000, v110
	v_lshlrev_b32_e32 v166, 16, v111
	v_and_b32_e32 v167, 0xffff0000, v111
	v_pk_fma_f32 v[168:169], v[152:153], v[160:161], v[168:169]
	v_pk_fma_f32 v[170:171], v[154:155], v[162:163], v[170:171]
	v_pk_fma_f32 v[172:173], v[156:157], v[164:165], v[172:173]
	v_pk_fma_f32 v[174:175], v[158:159], v[166:167], v[174:175]
	v_pk_mul_f32 v[160:161], v[168:169], s[36:37]
	v_pk_mul_f32 v[162:163], v[170:171], s[36:37]
	v_pk_mul_f32 v[164:165], v[172:173], s[36:37]
	v_pk_mul_f32 v[166:167], v[174:175], s[36:37]
	v_exp_f32_e32 v160, v160
	v_exp_f32_e32 v161, v161
	v_exp_f32_e32 v162, v162
	v_exp_f32_e32 v163, v163
	v_exp_f32_e32 v164, v164
	v_exp_f32_e32 v165, v165
	v_exp_f32_e32 v166, v166
	v_exp_f32_e32 v167, v167
	v_pk_add_f32 v[160:161], v[160:161], s[38:39]
	v_pk_add_f32 v[162:163], v[162:163], s[38:39]
	v_pk_add_f32 v[164:165], v[164:165], s[38:39]
	v_pk_add_f32 v[166:167], v[166:167], s[38:39]
	v_rcp_f32_e32 v160, v160
	v_rcp_f32_e32 v161, v161
	v_rcp_f32_e32 v162, v162
	v_rcp_f32_e32 v163, v163
	v_rcp_f32_e32 v164, v164
	v_rcp_f32_e32 v165, v165
; __device__ __forceinline__ unsigned pk2(float lo, float hi) { const f32v2_t v = {lo, hi}; const bf16v2_t b = __builtin_convertvector(v, bf16v2_t); return __builtin_bit_cast(unsigned, b); }
; __device__ __forceinline__ float lo16(unsigned u) { return __uint_as_float(u << 16); }
; __device__ __forceinline__ float hi16(unsigned u) { return __uint_as_float(u & 0xffff0000u); }
; __device__ __forceinline__ float siluf_(float x) { return x * __builtin_amdgcn_rcpf(1.0f + __expf(-x)); }
; __device__ __forceinline__ void prep_dn_finish(const float* cw, bf16_t* dq, bf16_t* dk, bf16_t* dv, const u32x4 (&raw)[4], int t, int ch) {
;     float a[8];
; #pragma unroll
;     for (int e = 0; e < 8; ++e) a[e] = 0.f;
; #pragma unroll
;     for (int k = 0; k < 4; ++k) {
;         const f32x4 w0 = *(const f32x4*)(cw + k * 3072 + ch), w1 = *(const f32x4*)(cw + k * 3072 + ch + 4);
;         a[0] += w0[0] * lo16(raw[k].x); a[1] += w0[1] * hi16(raw[k].x); a[2] += w0[2] * lo16(raw[k].y); a[3] += w0[3] * hi16(raw[k].y);
;         a[4] += w1[0] * lo16(raw[k].z); a[5] += w1[1] * hi16(raw[k].z); a[6] += w1[2] * lo16(raw[k].w); a[7] += w1[3] * hi16(raw[k].w); }
;     float ss = 0.f;
; #pragma unroll
;     for (int e = 0; e < 8; ++e) { a[e] = siluf_(a[e]); ss += a[e] * a[e]; }
;     ss += __shfl_xor(ss, 1); ss += __shfl_xor(ss, 2); ss += __shfl_xor(ss, 4); ss += __shfl_xor(ss, 8);
;     float sc = 1.0f;
;     if (ch < 2048) { sc = rsqrtf(ss + EPS); if (ch < 1024) sc *= 0.08838834764831845f; }
;     u32x4 w; w.x = pk2(a[0] * sc, a[1] * sc); w.y = pk2(a[2] * sc, a[3] * sc); w.z = pk2(a[4] * sc, a[5] * sc); w.w = pk2(a[6] * sc, a[7] * sc);
;     bf16_t* dst = (ch < 1024) ? dq : (ch < 2048 ? dk : dv);
;     *(u32x4*)(dst + (size_t)t * 1024 + (ch & 1023)) = w;
	v_rcp_f32_e32 v166, v166
	v_rcp_f32_e32 v167, v167
	v_pk_mul_f32 v[168:169], v[168:169], v[160:161]
	v_pk_mul_f32 v[170:171], v[170:171], v[162:163]
	v_pk_mul_f32 v[172:173], v[172:173], v[164:165]
	v_pk_mul_f32 v[174:175], v[174:175], v[166:167]
	v_pk_mul_f32 v[160:161], v[168:169], v[168:169]
	v_pk_fma_f32 v[160:161], v[170:171], v[170:171], v[160:161]
	v_pk_fma_f32 v[160:161], v[172:173], v[172:173], v[160:161]
	v_pk_fma_f32 v[160:161], v[174:175], v[174:175], v[160:161]
	s_nop 0
	v_add_f32_e32 v162, v160, v161
	s_nop 1
	v_add_f32_dpp v162, v162, v162 quad_perm:[1,0,3,2] row_mask:0xf bank_mask:0xf
	s_nop 1
	v_add_f32_dpp v162, v162, v162 quad_perm:[2,3,0,1] row_mask:0xf bank_mask:0xf
	s_nop 1
	v_add_f32_dpp v162, v162, v162 row_half_mirror row_mask:0xf bank_mask:0xf
	s_nop 1
	v_add_f32_dpp v162, v162, v162 row_mirror row_mask:0xf bank_mask:0xf
	v_add_f32_e32 v162, 0x358637bd, v162
	v_rsq_f32_e32 v162, v162
	s_nop 0
	v_mul_f32_e32 v162, 0x3db504f3, v162
	v_pk_mul_f32 v[168:169], v[168:169], v[162:163] op_sel_hi:[1,0]
	v_pk_mul_f32 v[170:171], v[170:171], v[162:163] op_sel_hi:[1,0]
	v_pk_mul_f32 v[172:173], v[172:173], v[162:163] op_sel_hi:[1,0]
	v_pk_mul_f32 v[174:175], v[174:175], v[162:163] op_sel_hi:[1,0]
	v_cvt_pk_bf16_f32 v56, v168, v169
	v_cvt_pk_bf16_f32 v57, v170, v171
	v_cvt_pk_bf16_f32 v58, v172, v173
	v_cvt_pk_bf16_f32 v59, v174, v175
	v_add_u32_e32 v13, 0x1f110000, v5
	global_store_dwordx4 v13, v[56:59], s[4:5]
	v_lshlrev_b32_e32 v160, 16, v112
	v_and_b32_e32 v161, 0xffff0000, v112
	v_lshlrev_b32_e32 v162, 16, v113
	v_and_b32_e32 v163, 0xffff0000, v113
	v_lshlrev_b32_e32 v164, 16, v114
	v_and_b32_e32 v165, 0xffff0000, v114
	v_lshlrev_b32_e32 v166, 16, v115
	v_and_b32_e32 v167, 0xffff0000, v115
	v_pk_mul_f32 v[168:169], v[128:129], v[160:161]
	v_pk_mul_f32 v[170:171], v[130:131], v[162:163]
	v_pk_mul_f32 v[172:173], v[132:133], v[164:165]
	v_pk_mul_f32 v[174:175], v[134:135], v[166:167]
	v_lshlrev_b32_e32 v160, 16, v116
	v_and_b32_e32 v161, 0xffff0000, v116
	v_lshlrev_b32_e32 v162, 16, v117
	v_and_b32_e32 v163, 0xffff0000, v117
	v_lshlrev_b32_e32 v164, 16, v118
	v_and_b32_e32 v165, 0xffff0000, v118
	v_lshlrev_b32_e32 v166, 16, v119
	v_and_b32_e32 v167, 0xffff0000, v119
	v_pk_fma_f32 v[168:169], v[136:137], v[160:161], v[168:169]
	v_pk_fma_f32 v[170:171], v[138:139], v[162:163], v[170:171]
	v_pk_fma_f32 v[172:173], v[140:141], v[164:165], v[172:173]
	v_pk_fma_f32 v[174:175], v[142:143], v[166:167], v[174:175]
	v_lshlrev_b32_e32 v160, 16, v120
	v_and_b32_e32 v161, 0xffff0000, v120
	v_lshlrev_b32_e32 v162, 16, v121
	v_and_b32_e32 v163, 0xffff0000, v121
	v_lshlrev_b32_e32 v164, 16, v122
	v_and_b32_e32 v165, 0xffff0000, v122
	v_lshlrev_b32_e32 v166, 16, v123
	v_and_b32_e32 v167, 0xffff0000, v123
	v_pk_fma_f32 v[168:169], v[144:145], v[160:161], v[168:169]
	v_pk_fma_f32 v[170:171], v[146:147], v[162:163], v[170:171]
	v_pk_fma_f32 v[172:173], v[148:149], v[164:165], v[172:173]
	v_pk_fma_f32 v[174:175], v[150:151], v[166:167], v[174:175]
	v_lshlrev_b32_e32 v160, 16, v124
	v_and_b32_e32 v161, 0xffff0000, v124
	v_lshlrev_b32_e32 v162, 16, v125
	v_and_b32_e32 v163, 0xffff0000, v125
	v_lshlrev_b32_e32 v164, 16, v126
	v_and_b32_e32 v165, 0xffff0000, v126
	v_lshlrev_b32_e32 v166, 16, v127
	v_and_b32_e32 v167, 0xffff0000, v127
	v_pk_fma_f32 v[168:169], v[152:153], v[160:161], v[168:169]
	v_pk_fma_f32 v[170:171], v[154:155], v[162:163], v[170:171]
	v_pk_fma_f32 v[172:173], v[156:157], v[164:165], v[172:173]
	v_pk_fma_f32 v[174:175], v[158:159], v[166:167], v[174:175]
	v_pk_mul_f32 v[160:161], v[168:169], s[36:37]
	v_pk_mul_f32 v[162:163], v[170:171], s[36:37]
	v_pk_mul_f32 v[164:165], v[172:173], s[36:37]
	v_pk_mul_f32 v[166:167], v[174:175], s[36:37]
	v_exp_f32_e32 v160, v160
	v_exp_f32_e32 v161, v161
	v_exp_f32_e32 v162, v162
	v_exp_f32_e32 v163, v163
	v_exp_f32_e32 v164, v164
	v_exp_f32_e32 v165, v165
	v_exp_f32_e32 v166, v166
	v_exp_f32_e32 v167, v167
	v_pk_add_f32 v[160:161], v[160:161], s[38:39]
	v_pk_add_f32 v[162:163], v[162:163], s[38:39]
	v_pk_add_f32 v[164:165], v[164:165], s[38:39]
	v_pk_add_f32 v[166:167], v[166:167], s[38:39]
	v_rcp_f32_e32 v160, v160
	v_rcp_f32_e32 v161, v161
	v_rcp_f32_e32 v162, v162
	v_rcp_f32_e32 v163, v163
	v_rcp_f32_e32 v164, v164
	v_rcp_f32_e32 v165, v165
	v_rcp_f32_e32 v166, v166
	v_rcp_f32_e32 v167, v167
	v_pk_mul_f32 v[168:169], v[168:169], v[160:161]
	v_pk_mul_f32 v[170:171], v[170:171], v[162:163]
	v_pk_mul_f32 v[172:173], v[172:173], v[164:165]
	v_pk_mul_f32 v[174:175], v[174:175], v[166:167]
	v_pk_mul_f32 v[160:161], v[168:169], v[168:169]
	v_pk_fma_f32 v[160:161], v[170:171], v[170:171], v[160:161]
	v_pk_fma_f32 v[160:161], v[172:173], v[172:173], v[160:161]
	v_pk_fma_f32 v[160:161], v[174:175], v[174:175], v[160:161]
	s_nop 0
	v_add_f32_e32 v162, v160, v161
	s_nop 1
	v_add_f32_dpp v162, v162, v162 quad_perm:[1,0,3,2] row_mask:0xf bank_mask:0xf
	s_nop 1
	v_add_f32_dpp v162, v162, v162 quad_perm:[2,3,0,1] row_mask:0xf bank_mask:0xf
	s_nop 1
	v_add_f32_dpp v162, v162, v162 row_half_mirror row_mask:0xf bank_mask:0xf
	s_nop 1
	v_add_f32_dpp v162, v162, v162 row_mirror row_mask:0xf bank_mask:0xf
	v_add_f32_e32 v162, 0x358637bd, v162
	v_rsq_f32_e32 v162, v162
	s_nop 0
	v_mul_f32_e32 v162, 0x3db504f3, v162
	v_pk_mul_f32 v[168:169], v[168:169], v[162:163] op_sel_hi:[1,0]
	v_pk_mul_f32 v[170:171], v[170:171], v[162:163] op_sel_hi:[1,0]
	v_pk_mul_f32 v[172:173], v[172:173], v[162:163] op_sel_hi:[1,0]
	v_pk_mul_f32 v[174:175], v[174:175], v[162:163] op_sel_hi:[1,0]
	v_cvt_pk_bf16_f32 v60, v168, v169
	v_cvt_pk_bf16_f32 v61, v170, v171
	v_cvt_pk_bf16_f32 v62, v172, v173
	v_cvt_pk_bf16_f32 v63, v174, v175
	v_add_u32_e32 v13, 0x1f118000, v5
	global_store_dwordx4 v13, v[60:63], s[4:5]
	s_cmp_lg_u32 s10, 0
	s_cbranch_scc1 .Ldnd_scan_done
; __device__ __forceinline__ float bf2f(bf16_t b) { return __uint_as_float(((unsigned)b) << 16); }
; __device__ __forceinline__ float sigmoidf_(float x) { return __builtin_amdgcn_rcpf(1.0f + __expf(-x)); }
; __device__ __forceinline__ float softplusf_(float x) { return fmaxf(x, 0.f) + __logf(1.0f + __expf(-fabsf(x))); }
;     template <class Tp> __device__ __forceinline__ Tp* W(size_t off) const { return (Tp*)(ws + off); }
; __device__ void dn_d1(const Ctx& c, int ip) {
;     ...
;     if (lt < 64) { const size_t rb = (size_t)(t0 + lt) * NP;
;         beta_s[lt] = sigmoidf_(bf2f(proj[rb + C_DNB + h]));
;         float g = -__expf(c.in(I_DNALOG)[c.layer * 8 + h]) * softplusf_(bf2f(proj[rb + C_DNA + h]) + c.in(I_DNDTB)[c.layer * 8 + h]);
; #pragma unroll
;         for (int d = 1; d < 64; d <<= 1) { const float o = __shfl_up(g, d); if ((lt & 63) >= d) g += o; }
;         gc_s[lt] = g; }
;     ...
;     if (lt == 0) c.W<float>(WS_DGL)[ch] = __expf(glast);
	v_add_u32_e32 v12, s15, v3
	s_mov_b32 s25, 0x7e00
	v_mul_lo_u32 v12, v12, s25
	s_lshl_b32 s22, s13, 1
	v_add_u32_e32 v12, s22, v12
	v_add_u32_e32 v13, 0x9c01800, v12
	v_add_u32_e32 v14, 0x9c01810, v12
	global_load_ushort v13, v13, s[4:5]
	global_load_ushort v14, v14, s[4:5]
	s_lshl_b32 s22, s16, 3
	s_add_u32 s22, s22, s13
	s_lshl_b32 s22, s22, 2
	s_load_dword s26, s[32:33], s22
	s_load_dword s27, s[34:35], s22
	s_waitcnt vmcnt(0) lgkmcnt(0)
	v_lshlrev_b32_e32 v13, 16, v13
	v_lshlrev_b32_e32 v14, 16, v14
	v_mul_f32_e32 v13, 0xbfb8aa3b, v13
	v_exp_f32_e32 v13, v13
	s_nop 0
	v_add_f32_e32 v13, 1.0, v13
	v_rcp_f32_e32 v13, v13
	v_add_f32_e32 v14, s27, v14
	s_mov_b32 s28, 0xbfb8aa3b
	v_mul_f32_e64 v15, |v14|, s28
	v_exp_f32_e32 v15, v15
	s_nop 0
	v_add_f32_e32 v15, 1.0, v15
	v_log_f32_e32 v15, v15
	v_max_f32_e32 v14, 0, v14
	v_mov_b32_e32 v12, s26
	v_mul_f32_e32 v12, 0x3fb8aa3b, v12
	v_exp_f32_e32 v12, v12
	v_fmac_f32_e32 v14, 0x3f317218, v15
	s_nop 0
	v_mul_f32_e64 v14, v14, -v12
	v_subrev_u32_e32 v12, 1, v3
	v_max_i32_e32 v12, 0, v12
	v_lshlrev_b32_e32 v12, 2, v12
	ds_bpermute_b32 v15, v12, v14
	v_cmp_le_u32_e32 vcc, 1, v3
	s_waitcnt lgkmcnt(0)
	v_add_f32_e32 v15, v14, v15
	v_cndmask_b32_e32 v14, v14, v15, vcc
	v_subrev_u32_e32 v12, 2, v3
	v_max_i32_e32 v12, 0, v12
	v_lshlrev_b32_e32 v12, 2, v12
	ds_bpermute_b32 v15, v12, v14
	v_cmp_le_u32_e32 vcc, 2, v3
	s_waitcnt lgkmcnt(0)
	v_add_f32_e32 v15, v14, v15
	v_cndmask_b32_e32 v14, v14, v15, vcc
	v_subrev_u32_e32 v12, 4, v3
	v_max_i32_e32 v12, 0, v12
	v_lshlrev_b32_e32 v12, 2, v12
	ds_bpermute_b32 v15, v12, v14
	v_cmp_le_u32_e32 vcc, 4, v3
	s_waitcnt lgkmcnt(0)
	v_add_f32_e32 v15, v14, v15
	v_cndmask_b32_e32 v14, v14, v15, vcc
	v_subrev_u32_e32 v12, 8, v3
	v_max_i32_e32 v12, 0, v12
	v_lshlrev_b32_e32 v12, 2, v12
	ds_bpermute_b32 v15, v12, v14
	v_cmp_le_u32_e32 vcc, 8, v3
	s_waitcnt lgkmcnt(0)
	v_add_f32_e32 v15, v14, v15
	v_cndmask_b32_e32 v14, v14, v15, vcc
	v_subrev_u32_e32 v12, 16, v3
	v_max_i32_e32 v12, 0, v12
	v_lshlrev_b32_e32 v12, 2, v12
	ds_bpermute_b32 v15, v12, v14
	v_cmp_le_u32_e32 vcc, 16, v3
	s_waitcnt lgkmcnt(0)
	v_add_f32_e32 v15, v14, v15
	v_cndmask_b32_e32 v14, v14, v15, vcc
	v_subrev_u32_e32 v12, 32, v3
	v_max_i32_e32 v12, 0, v12
	v_lshlrev_b32_e32 v12, 2, v12
	ds_bpermute_b32 v15, v12, v14
	v_cmp_le_u32_e32 vcc, 32, v3
	s_waitcnt lgkmcnt(0)
	v_add_f32_e32 v15, v14, v15
	v_cndmask_b32_e32 v14, v14, v15, vcc
	s_nop 1
	v_readlane_b32 s29, v14, 63
	v_lshl_add_u32 v12, v3, 2, s24
	ds_write_b32 v12, v14 offset:52224
	ds_write_b32 v12, v13 offset:52480
	v_sub_f32_e32 v15, s29, v14
	v_mul_f32_e32 v15, 0x3fb8aa3b, v15
	v_exp_f32_e32 v15, v15
	v_mul_f32_e32 v14, 0x3fb8aa3b, v14
	v_exp_f32_e32 v14, v14
	ds_write_b32 v12, v15 offset:52736
	v_mul_f32_e32 v14, v13, v14
	ds_write_b32 v12, v14 offset:52992
	v_mov_b32_e32 v15, s29
	v_mul_f32_e32 v15, 0x3fb8aa3b, v15
	v_exp_f32_e32 v15, v15
	s_lshl_b32 s22, s14, 2
	v_mov_b32_e32 v12, s22
	v_add_u32_e32 v12, 0x29900000, v12
	s_mov_b64 s[30:31], exec
	s_mov_b64 exec, 1
	global_store_dword v12, v15, s[4:5]
	s_mov_b64 exec, s[30:31]
